# PC/PD/PF epilogues: second half's gate/base tile loads issued together with the first half's (one memory round trip per epilogue instead of two)
# baseline (speedup 1.0000x reference)
; __device__ __forceinline__ void p0_pooleff_item(const float* wg, const float* scale, const float* wpb, bf16* WT, int item, int lane) {
;     ...
;     for (int j0 = 0; j0 < 128; j0 += 16) {
;         float b[16];
; #pragma unroll
;         for (int u = 0; u < 16; ++u) b[u] = bp[(size_t)(j0 + u) * 1024];
; #pragma unroll
;         for (int u = 0; u < 16; ++u) { const float bb = b[u] * sp[j0 + u];
;             a0 += wgp[0 * 128 + j0 + u] * bb; a1 += wgp[1 * 128 + j0 + u] * bb; a2 += wgp[2 * 128 + j0 + u] * bb; a3 += wgp[3 * 128 + j0 + u] * bb;
;             a4 += wgp[4 * 128 + j0 + u] * bb; a5 += wgp[5 * 128 + j0 + u] * bb; a6 += wgp[6 * 128 + j0 + u] * bb; a7 += wgp[7 * 128 + j0 + u] * bb; }
;     }
.LBB0_39:
	v_add_co_u32_e32 v10, vcc, s28, v66
	s_add_u32 s4, s14, s20
	s_nop 0
	v_addc_co_u32_e32 v11, vcc, 0, v67, vcc
	v_add_co_u32_e32 v12, vcc, s29, v66
	s_addc_u32 s5, s39, s21
	s_nop 0
	v_addc_co_u32_e32 v13, vcc, 0, v67, vcc
	v_add_co_u32_e32 v84, vcc, s30, v66
	s_add_u32 s8, s40, s20
	s_nop 0
	v_addc_co_u32_e32 v85, vcc, 0, v67, vcc
	v_add_co_u32_e32 v176, vcc, s31, v66
	s_addc_u32 s9, s41, s21
	s_nop 0
	v_addc_co_u32_e32 v177, vcc, 0, v67, vcc
	v_add_co_u32_e32 v178, vcc, s34, v66
	global_load_dword v74, v[66:67], off
	global_load_dwordx4 v[2:5], v75, s[4:5]
	global_load_dwordx4 v[6:9], v75, s[4:5] offset:16
	global_load_dwordx4 v[30:33], v75, s[4:5] offset:32
	global_load_dwordx4 v[34:37], v75, s[4:5] offset:48
	global_load_dword v180, v[10:11], off offset:-4096
	global_load_dword v181, v[10:11], off
	global_load_dword v182, v[12:13], off offset:-4096
	global_load_dword v183, v[12:13], off
	global_load_dwordx4 v[86:89], v75, s[8:9]
	global_load_dwordx4 v[104:107], v75, s[8:9] offset:512
	global_load_dwordx4 v[90:93], v75, s[8:9] offset:1024
	global_load_dwordx4 v[108:111], v75, s[8:9] offset:1536
	global_load_dwordx4 v[112:115], v75, s[8:9] offset:2048
	global_load_dwordx4 v[116:119], v75, s[8:9] offset:2560
	global_load_dwordx4 v[120:123], v75, s[8:9] offset:3072
	global_load_dwordx4 v[124:127], v75, s[8:9] offset:3584
	s_mov_b64 s[4:5], vcc
	global_load_dwordx4 v[128:131], v75, s[8:9] offset:16
	global_load_dwordx4 v[50:53], v75, s[8:9] offset:528
	global_load_dwordx4 v[132:135], v75, s[8:9] offset:1040
	global_load_dwordx4 v[54:57], v75, s[8:9] offset:1552
	global_load_dwordx4 v[136:139], v75, s[8:9] offset:2064
	global_load_dwordx4 v[58:61], v75, s[8:9] offset:2576
	global_load_dwordx4 v[140:143], v75, s[8:9] offset:3088
	global_load_dwordx4 v[62:65], v75, s[8:9] offset:3600
	global_load_dwordx4 v[144:147], v75, s[8:9] offset:32
	global_load_dwordx4 v[148:151], v75, s[8:9] offset:48
	global_load_dwordx4 v[38:41], v75, s[8:9] offset:544
	global_load_dwordx4 v[10:13], v75, s[8:9] offset:560
	global_load_dwordx4 v[152:155], v75, s[8:9] offset:1056
	global_load_dwordx4 v[156:159], v75, s[8:9] offset:1072
	global_load_dwordx4 v[42:45], v75, s[8:9] offset:1568
	global_load_dwordx4 v[14:17], v75, s[8:9] offset:1584
	global_load_dwordx4 v[160:163], v75, s[8:9] offset:2080
	global_load_dwordx4 v[164:167], v75, s[8:9] offset:2096
	global_load_dwordx4 v[46:49], v75, s[8:9] offset:2592
	global_load_dwordx4 v[18:21], v75, s[8:9] offset:2608
	global_load_dwordx4 v[168:171], v75, s[8:9] offset:3104
	global_load_dwordx4 v[172:175], v75, s[8:9] offset:3120
	global_load_dwordx4 v[26:29], v75, s[8:9] offset:3616
	global_load_dwordx4 v[22:25], v75, s[8:9] offset:3632
	global_load_dword v195, v[84:85], off offset:-4096
	global_load_dword v196, v[84:85], off
	global_load_dword v198, v[176:177], off offset:-4096
	global_load_dword v199, v[176:177], off
	v_add_co_u32_e32 v84, vcc, s35, v66
	s_mov_b64 s[8:9], vcc
	v_addc_co_u32_e64 v179, vcc, 0, v67, s[4:5]
	v_add_co_u32_e32 v176, vcc, s36, v66
	global_load_dword v200, v[178:179], off offset:-4096
	global_load_dword v201, v[178:179], off
	v_addc_co_u32_e32 v177, vcc, 0, v67, vcc
	v_addc_co_u32_e64 v85, s[4:5], 0, v67, s[8:9]
	v_add_co_u32_e32 v178, vcc, s37, v66
	global_load_dword v202, v[84:85], off offset:-4096
	global_load_dword v203, v[84:85], off
	global_load_dword v204, v[176:177], off
	s_nop 0
	global_load_dword v177, v[176:177], off offset:-4096
	v_addc_co_u32_e32 v179, vcc, 0, v67, vcc
	global_load_dword v179, v[178:179], off
	s_add_i32 s42, s42, 16
	s_add_u32 s20, s20, 64
	s_addc_u32 s21, s21, 0
	s_cmpk_lt_u32 s42, 0x70
	v_lshl_add_u64 v[66:67], v[66:67], 0, s[16:17]
	s_waitcnt vmcnt(8)
	v_mov_b32_e32 v197, v38
	v_mov_b32_e32 v38, v145
	v_mov_b32_e32 v145, v40
	v_mov_b32_e32 v40, v147
	v_mov_b32_e32 v184, v86
	v_mov_b32_e32 v185, v104
	v_mov_b32_e32 v188, v90
	v_mov_b32_e32 v189, v108
	v_mov_b32_e32 v192, v112
	v_mul_f32_e32 v74, v74, v2
	v_mov_b32_e32 v193, v116
	v_mov_b32_e32 v116, v113
	v_mov_b32_e32 v112, v114
	v_mov_b32_e32 v113, v118
	v_mov_b32_e32 v118, v115
	v_mov_b32_e32 v114, v120
	v_mov_b32_e32 v115, v124
	v_mul_f32_e32 v176, v180, v3
	v_mov_b32_e32 v104, v87
	v_mov_b32_e32 v108, v91
	v_mov_b32_e32 v124, v121
	v_pk_fma_f32 v[82:83], v[184:185], v[74:75], v[82:83] op_sel_hi:[1,0,1]
	v_pk_fma_f32 v[72:73], v[74:75], v[188:189], v[72:73] op_sel_hi:[0,1,1]
	v_pk_fma_f32 v[70:71], v[74:75], v[192:193], v[70:71] op_sel_hi:[0,1,1]
	v_pk_fma_f32 v[68:69], v[74:75], v[114:115], v[68:69] op_sel_hi:[0,1,1]
	v_mul_f32_e32 v178, v181, v4
	v_mov_b32_e32 v186, v88
	v_mov_b32_e32 v187, v106
	v_mov_b32_e32 v190, v92
	v_mov_b32_e32 v191, v110
	v_mov_b32_e32 v120, v122
	v_mov_b32_e32 v121, v126
	s_waitcnt vmcnt(1)
	v_pk_fma_f32 v[82:83], v[104:105], v[176:177], v[82:83] op_sel_hi:[1,0,1]
	v_pk_fma_f32 v[72:73], v[176:177], v[108:109], v[72:73] op_sel_hi:[0,1,1]
	v_pk_fma_f32 v[70:71], v[176:177], v[116:117], v[70:71] op_sel_hi:[0,1,1]
	v_pk_fma_f32 v[68:69], v[176:177], v[124:125], v[68:69] op_sel_hi:[0,1,1]
	v_mul_f32_e32 v180, v182, v5
	v_mov_b32_e32 v106, v89
	v_mov_b32_e32 v110, v93
	v_mov_b32_e32 v126, v123
	s_waitcnt vmcnt(0)
; #define GAS __attribute__((address_space(1)))
; __device__ __forceinline__ unsigned pk2(float lo, float hi) { f32x2p v = {lo, hi}; bf16x2p b = __builtin_convertvector(v, bf16x2p); return __builtin_bit_cast(unsigned, b); }
; __device__ __forceinline__ void p0_pooleff_item(const float* wg, const float* scale, const float* wpb, bf16* WT, int item, int lane) {
;     ...
;     for (int j0 = 0; j0 < 128; j0 += 16) {
;         float b[16];
; #pragma unroll
;         for (int u = 0; u < 16; ++u) b[u] = bp[(size_t)(j0 + u) * 1024];
; #pragma unroll
;         for (int u = 0; u < 16; ++u) { const float bb = b[u] * sp[j0 + u];
;             a0 += wgp[0 * 128 + j0 + u] * bb; a1 += wgp[1 * 128 + j0 + u] * bb; a2 += wgp[2 * 128 + j0 + u] * bb; a3 += wgp[3 * 128 + j0 + u] * bb;
;             a4 += wgp[4 * 128 + j0 + u] * bb; a5 += wgp[5 * 128 + j0 + u] * bb; a6 += wgp[6 * 128 + j0 + u] * bb; a7 += wgp[7 * 128 + j0 + u] * bb; }
;     }
;     v4u o; o.x = pk2(a0, a1); o.y = pk2(a2, a3); o.z = pk2(a4, a5); o.w = pk2(a6, a7);
;     *(GAS v4u*)(WT + (size_t)n * 1024 + g * 128 + cblk * 8) = o;
	v_pk_fma_f32 v[82:83], v[186:187], v[178:179], v[82:83] op_sel_hi:[1,0,1]
	v_pk_fma_f32 v[72:73], v[178:179], v[190:191], v[72:73] op_sel_hi:[0,1,1]
	v_pk_fma_f32 v[70:71], v[178:179], v[112:113], v[70:71] op_sel_hi:[0,1,1]
	v_pk_fma_f32 v[68:69], v[178:179], v[120:121], v[68:69] op_sel_hi:[0,1,1]
	v_mul_f32_e32 v182, v183, v6
	v_mov_b32_e32 v122, v128
	v_mov_b32_e32 v123, v50
	v_mov_b32_e32 v50, v129
	v_mov_b32_e32 v128, v130
	v_mov_b32_e32 v129, v52
	v_mov_b32_e32 v52, v131
	v_mov_b32_e32 v130, v132
	v_mov_b32_e32 v131, v54
	v_mov_b32_e32 v54, v133
	v_mov_b32_e32 v132, v134
	v_mov_b32_e32 v133, v56
	v_mov_b32_e32 v56, v135
	v_mov_b32_e32 v134, v136
	v_mov_b32_e32 v135, v58
	v_mov_b32_e32 v58, v137
	v_mov_b32_e32 v136, v138
	v_mov_b32_e32 v137, v60
	v_mov_b32_e32 v60, v139
	v_mov_b32_e32 v138, v140
	v_mov_b32_e32 v139, v62
	v_pk_fma_f32 v[82:83], v[106:107], v[180:181], v[82:83] op_sel_hi:[1,0,1]
	v_pk_fma_f32 v[72:73], v[180:181], v[110:111], v[72:73] op_sel_hi:[0,1,1]
	v_pk_fma_f32 v[70:71], v[180:181], v[118:119], v[70:71] op_sel_hi:[0,1,1]
	v_pk_fma_f32 v[68:69], v[180:181], v[126:127], v[68:69] op_sel_hi:[0,1,1]
	v_mov_b32_e32 v62, v141
	v_mov_b32_e32 v140, v142
	v_mul_f32_e32 v142, v195, v7
	v_pk_fma_f32 v[82:83], v[122:123], v[182:183], v[82:83] op_sel_hi:[1,0,1]
	v_pk_fma_f32 v[72:73], v[182:183], v[130:131], v[72:73] op_sel_hi:[0,1,1]
	v_pk_fma_f32 v[70:71], v[182:183], v[134:135], v[70:71] op_sel_hi:[0,1,1]
	v_pk_fma_f32 v[68:69], v[182:183], v[138:139], v[68:69] op_sel_hi:[0,1,1]
	v_mov_b32_e32 v141, v64
	v_mul_f32_e32 v8, v196, v8
	v_pk_fma_f32 v[50:51], v[50:51], v[142:143], v[82:83] op_sel_hi:[1,0,1]
	v_pk_fma_f32 v[54:55], v[142:143], v[54:55], v[72:73] op_sel_hi:[0,1,1]
	v_pk_fma_f32 v[58:59], v[142:143], v[58:59], v[70:71] op_sel_hi:[0,1,1]
	v_pk_fma_f32 v[62:63], v[142:143], v[62:63], v[68:69] op_sel_hi:[0,1,1]
	v_mov_b32_e32 v64, v143
	v_mul_f32_e32 v74, v198, v9
	v_pk_fma_f32 v[50:51], v[128:129], v[8:9], v[50:51] op_sel_hi:[1,0,1]
	v_pk_fma_f32 v[54:55], v[8:9], v[132:133], v[54:55] op_sel_hi:[0,1,1]
	v_pk_fma_f32 v[58:59], v[8:9], v[136:137], v[58:59] op_sel_hi:[0,1,1]
	v_pk_fma_f32 v[8:9], v[8:9], v[140:141], v[62:63] op_sel_hi:[0,1,1]
	v_mov_b32_e32 v196, v144
	v_mov_b32_e32 v144, v146
	v_mov_b32_e32 v4, v148
	v_mov_b32_e32 v5, v10
	v_mov_b32_e32 v10, v149
	v_mov_b32_e32 v2, v150
	v_mov_b32_e32 v3, v12
	v_mov_b32_e32 v12, v151
	v_mov_b32_e32 v146, v152
	v_mov_b32_e32 v147, v42
	v_mov_b32_e32 v148, v154
	v_mov_b32_e32 v149, v44
	v_mov_b32_e32 v44, v155
	v_mov_b32_e32 v150, v160
	v_mov_b32_e32 v151, v46
	v_mov_b32_e32 v154, v168
	v_mov_b32_e32 v155, v26
	v_mul_f32_e32 v30, v199, v30
	v_pk_fma_f32 v[50:51], v[52:53], v[74:75], v[50:51] op_sel_hi:[1,0,1]
	v_pk_fma_f32 v[52:53], v[74:75], v[56:57], v[54:55] op_sel_hi:[0,1,1]
	v_pk_fma_f32 v[54:55], v[74:75], v[60:61], v[58:59] op_sel_hi:[0,1,1]
	v_pk_fma_f32 v[8:9], v[74:75], v[64:65], v[8:9] op_sel_hi:[0,1,1]
	v_mov_b32_e32 v42, v153
	v_mov_b32_e32 v46, v161
	v_mov_b32_e32 v26, v169
	v_mul_f32_e32 v104, v200, v31
	v_pk_fma_f32 v[50:51], v[196:197], v[30:31], v[50:51] op_sel_hi:[1,0,1]
	v_pk_fma_f32 v[52:53], v[30:31], v[146:147], v[52:53] op_sel_hi:[0,1,1]
	v_pk_fma_f32 v[54:55], v[30:31], v[150:151], v[54:55] op_sel_hi:[0,1,1]
	v_pk_fma_f32 v[8:9], v[30:31], v[154:155], v[8:9] op_sel_hi:[0,1,1]
	v_mov_b32_e32 v84, v156
	v_mov_b32_e32 v85, v14
	v_mov_b32_e32 v14, v157
	v_mov_b32_e32 v152, v162
	v_mov_b32_e32 v153, v48
	v_mov_b32_e32 v156, v170
	v_mov_b32_e32 v157, v28
	v_mul_f32_e32 v32, v201, v32
	v_pk_fma_f32 v[30:31], v[38:39], v[104:105], v[50:51] op_sel_hi:[1,0,1]
	v_pk_fma_f32 v[38:39], v[104:105], v[42:43], v[52:53] op_sel_hi:[0,1,1]
	v_pk_fma_f32 v[42:43], v[104:105], v[46:47], v[54:55] op_sel_hi:[0,1,1]
	v_pk_fma_f32 v[8:9], v[104:105], v[26:27], v[8:9] op_sel_hi:[0,1,1]
	v_mov_b32_e32 v48, v163
	v_mov_b32_e32 v28, v171
	v_mul_f32_e32 v108, v202, v33
	v_pk_fma_f32 v[26:27], v[144:145], v[32:33], v[30:31] op_sel_hi:[1,0,1]
	v_pk_fma_f32 v[30:31], v[32:33], v[148:149], v[38:39] op_sel_hi:[0,1,1]
	v_pk_fma_f32 v[38:39], v[32:33], v[152:153], v[42:43] op_sel_hi:[0,1,1]
	v_pk_fma_f32 v[8:9], v[32:33], v[156:157], v[8:9] op_sel_hi:[0,1,1]
	v_mov_b32_e32 v88, v164
	v_mov_b32_e32 v89, v18
	v_mov_b32_e32 v92, v172
	v_mov_b32_e32 v93, v22
	v_mul_f32_e32 v34, v203, v34
	v_pk_fma_f32 v[26:27], v[40:41], v[108:109], v[26:27] op_sel_hi:[1,0,1]
	v_pk_fma_f32 v[30:31], v[108:109], v[44:45], v[30:31] op_sel_hi:[0,1,1]
	v_pk_fma_f32 v[32:33], v[108:109], v[48:49], v[38:39] op_sel_hi:[0,1,1]
	v_pk_fma_f32 v[8:9], v[108:109], v[28:29], v[8:9] op_sel_hi:[0,1,1]
	v_mov_b32_e32 v18, v165
	v_mov_b32_e32 v22, v173
	v_mul_f32_e32 v106, v177, v35
	v_pk_fma_f32 v[4:5], v[4:5], v[34:35], v[26:27] op_sel_hi:[1,0,1]
	v_pk_fma_f32 v[26:27], v[34:35], v[84:85], v[30:31] op_sel_hi:[0,1,1]
	v_pk_fma_f32 v[28:29], v[34:35], v[88:89], v[32:33] op_sel_hi:[0,1,1]
	v_pk_fma_f32 v[8:9], v[34:35], v[92:93], v[8:9] op_sel_hi:[0,1,1]
	v_mov_b32_e32 v6, v158
	v_mov_b32_e32 v7, v16
	v_mov_b32_e32 v86, v166
	v_mov_b32_e32 v87, v20
	v_mov_b32_e32 v90, v174
	v_mov_b32_e32 v91, v24
	v_mul_f32_e32 v36, v204, v36
	v_pk_fma_f32 v[4:5], v[10:11], v[106:107], v[4:5] op_sel_hi:[1,0,1]
	v_pk_fma_f32 v[10:11], v[106:107], v[14:15], v[26:27] op_sel_hi:[0,1,1]
	v_pk_fma_f32 v[14:15], v[106:107], v[18:19], v[28:29] op_sel_hi:[0,1,1]
	v_pk_fma_f32 v[8:9], v[106:107], v[22:23], v[8:9] op_sel_hi:[0,1,1]
	v_mov_b32_e32 v16, v159
	v_mov_b32_e32 v20, v167
	v_mov_b32_e32 v24, v175
	v_mul_f32_e32 v110, v179, v37
	v_pk_fma_f32 v[2:3], v[2:3], v[36:37], v[4:5] op_sel_hi:[1,0,1]
	v_pk_fma_f32 v[4:5], v[36:37], v[6:7], v[10:11] op_sel_hi:[0,1,1]
	v_pk_fma_f32 v[6:7], v[36:37], v[86:87], v[14:15] op_sel_hi:[0,1,1]
	v_pk_fma_f32 v[8:9], v[36:37], v[90:91], v[8:9] op_sel_hi:[0,1,1]
	v_pk_fma_f32 v[82:83], v[12:13], v[110:111], v[2:3] op_sel_hi:[1,0,1]
	v_pk_fma_f32 v[72:73], v[110:111], v[16:17], v[4:5] op_sel_hi:[0,1,1]
	v_pk_fma_f32 v[70:71], v[110:111], v[20:21], v[6:7] op_sel_hi:[0,1,1]
	v_pk_fma_f32 v[68:69], v[110:111], v[24:25], v[8:9] op_sel_hi:[0,1,1]
	s_cbranch_scc1 .LBB0_39
	s_lshl_b32 s4, s38, 6
	s_and_b32 s4, s4, 0x3c0
	v_or_b32_e32 v6, s4, v194
	v_lshlrev_b32_e32 v74, 11, v6
	v_lshl_add_u64 v[6:7], s[12:13], 0, v[74:75]
	v_lshl_add_u64 v[6:7], s[18:19], 1, v[6:7]
	s_and_b32 s14, s38, 0xf0
	v_cvt_pk_bf16_f32 v2, v82, v83
	v_cvt_pk_bf16_f32 v3, v72, v73
	v_cvt_pk_bf16_f32 v4, v70, v71
	v_cvt_pk_bf16_f32 v5, v68, v69
	v_lshl_add_u64 v[6:7], v[6:7], 0, s[14:15]
	global_store_dwordx4 v[6:7], v[2:5], off
	s_branch .LBB0_15

; __device__ __forceinline__ unsigned cvt_pk_bf16(float lo, float hi) { f32x2c v = {lo, hi}; bf16x2c b = __builtin_convertvector(v, bf16x2c); return __builtin_bit_cast(unsigned, b); }
; __device__ __forceinline__ float bf_lo(unsigned w) { return __uint_as_float(w << 16); }
; __device__ __forceinline__ float bf_hi(unsigned w) { return __uint_as_float(w & 0xffff0000u); }
;     __device__ __forceinline__ void operator()(f32x4 (&acc)[2][2][4][2], const Unit& u, int wr, int wc, int fr, int fq) const {
;         const int row0 = u.pm * BM + wr * 64 + fr, col0 = u.pn * BM + wc * 32 + 8 * fq;
;         const int gcol = (u.seg == 0 ? 1280 : 2304) + col0;
; #pragma unroll
;         for (int ai = 0; ai < 2; ++ai) {
;             u32x4 ga[4][2];
; #pragma unroll
;             for (int m = 0; m < 4; ++m)
; #pragma unroll
;                 for (int bj = 0; bj < 2; ++bj) ga[m][bj] = *(const u32x4*)(P + (size_t)(row0 + ai * HALF + m * 16) * 3328 + gcol + bj * HALF);
; #pragma unroll
;             for (int m = 0; m < 4; ++m)
; #pragma unroll
;                 for (int bj = 0; bj < 2; ++bj) {
;                     const u32x4 g = ga[m][bj];
;                     const f32x4 a0 = (f32x4){bf_lo(g.x), bf_hi(g.x), bf_lo(g.y), bf_hi(g.y)}, a1 = (f32x4){bf_lo(g.z), bf_hi(g.z), bf_lo(g.w), bf_hi(g.w)};
;                     acc[ai][bj][m][0] *= a0; acc[ai][bj][m][1] *= a1;
;                     if (u.seg != 0) {
;                         const f32x4 v0 = acc[ai][bj][m][0], v1 = acc[ai][bj][m][1];
;                         u32x4 w; w.x = cvt_pk_bf16(v0[0], v0[1]); w.y = cvt_pk_bf16(v0[2], v0[3]); w.z = cvt_pk_bf16(v1[0], v1[1]); w.w = cvt_pk_bf16(v1[2], v1[3]);
;                         *(u32x4*)(O + (size_t)(row0 + ai * HALF + m * 16) * 1024 + col0 + bj * HALF) = w;
;                     }
.LBB0_519:
	s_cmp_lg_u32 s27, 0
	s_cselect_b64 s[72:73], -1, 0
	s_cmp_eq_u32 s27, 0
	v_lshl_add_u32 v178, s29, 8, v67
	v_lshl_or_b32 v176, s28, 8, v191
	s_cselect_b64 s[28:29], -1, 0
	s_and_b64 vcc, s[28:29], exec
	s_movk_i32 s27, 0x900
	s_cselect_b32 s27, 0x500, s27
	v_add_u32_e32 v132, s27, v176
	v_ashrrev_i32_e32 v133, 31, v132
	v_lshl_add_u64 v[180:181], v[132:133], 1, s[94:95]
	v_mad_i64_i32 v[132:133], s[28:29], v178, s82, v[180:181]
	v_or_b32_e32 v186, 16, v178
	global_load_dwordx4 v[204:207], v[132:133], off
	global_load_dwordx4 v[156:159], v[132:133], off offset:256
	v_mad_i64_i32 v[132:133], s[28:29], v186, s82, v[180:181]
	v_or_b32_e32 v184, 32, v178
	global_load_dwordx4 v[152:155], v[132:133], off
	global_load_dwordx4 v[148:151], v[132:133], off offset:256
	v_mad_i64_i32 v[132:133], s[28:29], v184, s82, v[180:181]
	v_or_b32_e32 v182, 48, v178
	global_load_dwordx4 v[144:147], v[132:133], off
	global_load_dwordx4 v[140:143], v[132:133], off offset:256
	v_mad_i64_i32 v[132:133], s[28:29], v182, s82, v[180:181]
	global_load_dwordx4 v[136:139], v[132:133], off
	s_nop 0
	global_load_dwordx4 v[132:135], v[132:133], off offset:256
	v_add_u32_e32 v193, 0x80, v178
	v_mad_i64_i32 v[236:237], s[98:99], v193, s82, v[180:181]
	global_load_dwordx4 v[212:215], v[236:237], off
	global_load_dwordx4 v[216:219], v[236:237], off offset:256
	v_add_u32_e32 v193, 0x90, v178
	v_mad_i64_i32 v[236:237], s[98:99], v193, s82, v[180:181]
	global_load_dwordx4 v[220:223], v[236:237], off
	global_load_dwordx4 v[224:227], v[236:237], off offset:256
	v_add_u32_e32 v193, 0xa0, v178
	v_mad_i64_i32 v[236:237], s[98:99], v193, s82, v[180:181]
	global_load_dwordx4 v[228:231], v[236:237], off
	global_load_dwordx4 v[232:235], v[236:237], off offset:256
	v_add_u32_e32 v193, 0xb0, v178
	v_mad_i64_i32 v[236:237], s[98:99], v193, s82, v[180:181]
	global_load_dwordx4 v[244:247], v[236:237], off
	global_load_dwordx4 v[248:251], v[236:237], off offset:256
	v_ashrrev_i32_e32 v179, 31, v178
	v_lshlrev_b64 v[188:189], 11, v[178:179]
	v_ashrrev_i32_e32 v177, 31, v176
	v_lshl_add_u64 v[188:189], s[86:87], 0, v[188:189]
	v_lshl_add_u64 v[188:189], v[176:177], 1, v[188:189]
	s_waitcnt vmcnt(8)
	v_lshlrev_b32_e32 v208, 16, v204
	v_and_b32_e32 v209, 0xffff0000, v204
	v_lshlrev_b32_e32 v204, 16, v205
	v_and_b32_e32 v205, 0xffff0000, v205
	v_lshlrev_b32_e32 v210, 16, v206
	v_and_b32_e32 v211, 0xffff0000, v206
	v_lshlrev_b32_e32 v206, 16, v207
	v_and_b32_e32 v207, 0xffff0000, v207
	v_pk_mul_f32 v[130:131], v[130:131], v[204:205]
	v_pk_mul_f32 v[128:129], v[128:129], v[208:209]
	v_pk_mul_f32 v[126:127], v[126:127], v[206:207]
	v_pk_mul_f32 v[124:125], v[124:125], v[210:211]
	s_cbranch_vccnz .LBB0_521
	v_cvt_pk_bf16_f32 v204, v128, v129
	v_cvt_pk_bf16_f32 v205, v130, v131
	v_cvt_pk_bf16_f32 v206, v124, v125
	v_cvt_pk_bf16_f32 v207, v126, v127
	global_store_dwordx4 v[188:189], v[204:207], off

;     __device__ __forceinline__ void operator()(f32x4 (&acc)[2][2][4][2], const Unit& u, int wr, int wc, int fr, int fq) const {
;     ...
;         const int gcol = (u.seg == 0 ? 1280 : 2304) + col0;
; #pragma unroll
;         for (int ai = 0; ai < 2; ++ai) {
;             u32x4 ga[4][2];
; #pragma unroll
;             for (int m = 0; m < 4; ++m)
; #pragma unroll
;                 for (int bj = 0; bj < 2; ++bj) ga[m][bj] = *(const u32x4*)(P + (size_t)(row0 + ai * HALF + m * 16) * 3328 + gcol + bj * HALF);
; #pragma unroll
.LBB0_535:
	v_add_u32_e32 v204, 0x80, v178
	s_nop 0
	v_mad_i64_i32 v[132:133], s[28:29], v204, s82, v[180:181]
	v_add_u32_e32 v184, 0x90, v178
	s_cbranch_vccnz .Lpc_gate_w0
	s_waitcnt vmcnt(8)
	s_branch .Lpc_gate_wd

; __device__ __forceinline__ unsigned cvt_pk_bf16(float lo, float hi) { f32x2c v = {lo, hi}; bf16x2c b = __builtin_convertvector(v, bf16x2c); return __builtin_bit_cast(unsigned, b); }
; __device__ __forceinline__ float bf_lo(unsigned w) { return __uint_as_float(w << 16); }
; __device__ __forceinline__ float bf_hi(unsigned w) { return __uint_as_float(w & 0xffff0000u); }
;     __device__ __forceinline__ void operator()(f32x4 (&acc)[2][2][4][2], const Unit& u, int wr, int wc, int fr, int fq) const {
;     ...
;                 for (int bj = 0; bj < 2; ++bj) ga[m][bj] = *(const u32x4*)(P + (size_t)(row0 + ai * HALF + m * 16) * 3328 + gcol + bj * HALF);
; #pragma unroll
;             for (int m = 0; m < 4; ++m)
; #pragma unroll
;                 for (int bj = 0; bj < 2; ++bj) {
;                     const u32x4 g = ga[m][bj];
;                     const f32x4 a0 = (f32x4){bf_lo(g.x), bf_hi(g.x), bf_lo(g.y), bf_hi(g.y)}, a1 = (f32x4){bf_lo(g.z), bf_hi(g.z), bf_lo(g.w), bf_hi(g.w)};
;                     acc[ai][bj][m][0] *= a0; acc[ai][bj][m][1] *= a1;
;                     if (u.seg != 0) {
;                         const f32x4 v0 = acc[ai][bj][m][0], v1 = acc[ai][bj][m][1];
;                         u32x4 w; w.x = cvt_pk_bf16(v0[0], v0[1]); w.y = cvt_pk_bf16(v0[2], v0[3]); w.z = cvt_pk_bf16(v1[0], v1[1]); w.w = cvt_pk_bf16(v1[2], v1[3]);
;                         *(u32x4*)(O + (size_t)(row0 + ai * HALF + m * 16) * 1024 + col0 + bj * HALF) = w;
;                     }
.Lpc_gate_wd:
	v_mov_b32_e32 v186, v212
	v_mov_b32_e32 v187, v213
	v_mov_b32_e32 v188, v214
	v_mov_b32_e32 v189, v215
	v_mov_b32_e32 v156, v216
	v_mov_b32_e32 v157, v217
	v_mov_b32_e32 v158, v218
	v_mov_b32_e32 v159, v219
	v_mad_i64_i32 v[132:133], s[28:29], v184, s82, v[180:181]
	v_add_u32_e32 v182, 0xa0, v178
	v_mov_b32_e32 v152, v220
	v_mov_b32_e32 v153, v221
	v_mov_b32_e32 v154, v222
	v_mov_b32_e32 v155, v223
	v_mov_b32_e32 v148, v224
	v_mov_b32_e32 v149, v225
	v_mov_b32_e32 v150, v226
	v_mov_b32_e32 v151, v227
	v_mad_i64_i32 v[132:133], s[28:29], v182, s82, v[180:181]
	v_add_u32_e32 v178, 0xb0, v178
	v_mov_b32_e32 v144, v228
	v_mov_b32_e32 v145, v229
	v_mov_b32_e32 v146, v230
	v_mov_b32_e32 v147, v231
	v_mov_b32_e32 v140, v232
	v_mov_b32_e32 v141, v233
	v_mov_b32_e32 v142, v234
	v_mov_b32_e32 v143, v235
	v_mad_i64_i32 v[132:133], s[28:29], v178, s82, v[180:181]
	v_mov_b32_e32 v136, v244
	v_mov_b32_e32 v137, v245
	v_mov_b32_e32 v138, v246
	v_mov_b32_e32 v139, v247
	s_nop 0
	v_mov_b32_e32 v132, v248
	v_mov_b32_e32 v133, v249
	v_mov_b32_e32 v134, v250
	v_mov_b32_e32 v135, v251
	v_ashrrev_i32_e32 v205, 31, v204
	v_lshlrev_b64 v[180:181], 11, v[204:205]
	v_lshl_add_u64 v[180:181], s[86:87], 0, v[180:181]
	s_and_b64 vcc, exec, s[38:39]
	v_lshl_add_u64 v[180:181], v[176:177], 1, v[180:181]
	v_lshlrev_b32_e32 v204, 16, v186
	v_and_b32_e32 v205, 0xffff0000, v186
	v_lshlrev_b32_e32 v186, 16, v187
	v_and_b32_e32 v187, 0xffff0000, v187
	v_lshlrev_b32_e32 v206, 16, v188
	v_and_b32_e32 v207, 0xffff0000, v188
	v_lshlrev_b32_e32 v188, 16, v189
	v_and_b32_e32 v189, 0xffff0000, v189
	v_pk_mul_f32 v[64:65], v[64:65], v[186:187]
	v_pk_mul_f32 v[62:63], v[62:63], v[204:205]
	v_pk_mul_f32 v[60:61], v[60:61], v[188:189]
	v_pk_mul_f32 v[58:59], v[58:59], v[206:207]
	s_cbranch_vccnz .LBB0_537
	v_cvt_pk_bf16_f32 v186, v62, v63
	v_cvt_pk_bf16_f32 v187, v64, v65
	v_cvt_pk_bf16_f32 v188, v58, v59
	v_cvt_pk_bf16_f32 v189, v60, v61
	global_store_dwordx4 v[180:181], v[186:189], off
.LBB0_537:
	s_nop 0
	v_lshlrev_b32_e32 v186, 16, v156
	v_and_b32_e32 v187, 0xffff0000, v156
	v_lshlrev_b32_e32 v156, 16, v157
	v_and_b32_e32 v157, 0xffff0000, v157
	v_lshlrev_b32_e32 v188, 16, v158
	v_and_b32_e32 v189, 0xffff0000, v158
	v_lshlrev_b32_e32 v158, 16, v159
	v_and_b32_e32 v159, 0xffff0000, v159
	v_pk_mul_f32 v[32:33], v[32:33], v[156:157]
	v_pk_mul_f32 v[30:31], v[30:31], v[186:187]
	v_pk_mul_f32 v[28:29], v[28:29], v[158:159]
	s_and_b64 vcc, exec, s[38:39]
	v_pk_mul_f32 v[26:27], v[26:27], v[188:189]
	s_cbranch_vccnz .LBB0_539
	v_cvt_pk_bf16_f32 v156, v30, v31
	v_cvt_pk_bf16_f32 v157, v32, v33
	v_cvt_pk_bf16_f32 v158, v26, v27
	v_cvt_pk_bf16_f32 v159, v28, v29
	global_store_dwordx4 v[180:181], v[156:159], off offset:256
.LBB0_539:
	v_ashrrev_i32_e32 v185, 31, v184
	s_nop 0
	v_lshlrev_b64 v[156:157], 11, v[184:185]
	v_lshlrev_b32_e32 v158, 16, v152
	v_and_b32_e32 v159, 0xffff0000, v152
	v_lshlrev_b32_e32 v152, 16, v153
	v_and_b32_e32 v153, 0xffff0000, v153
	v_lshlrev_b32_e32 v180, 16, v154
	v_and_b32_e32 v181, 0xffff0000, v154
	v_lshlrev_b32_e32 v154, 16, v155
	v_and_b32_e32 v155, 0xffff0000, v155
	v_pk_mul_f32 v[56:57], v[56:57], v[152:153]
	v_lshl_add_u64 v[152:153], s[86:87], 0, v[156:157]
	v_pk_mul_f32 v[54:55], v[54:55], v[158:159]
	v_pk_mul_f32 v[52:53], v[52:53], v[154:155]
	v_pk_mul_f32 v[50:51], v[50:51], v[180:181]
	s_and_b64 vcc, exec, s[38:39]
	v_lshl_add_u64 v[152:153], v[176:177], 1, v[152:153]
	s_cbranch_vccnz .LBB0_541
	v_cvt_pk_bf16_f32 v154, v54, v55
	v_cvt_pk_bf16_f32 v155, v56, v57
	v_cvt_pk_bf16_f32 v156, v50, v51
	v_cvt_pk_bf16_f32 v157, v52, v53
	global_store_dwordx4 v[152:153], v[154:157], off
; __device__ __forceinline__ unsigned cvt_pk_bf16(float lo, float hi) { f32x2c v = {lo, hi}; bf16x2c b = __builtin_convertvector(v, bf16x2c); return __builtin_bit_cast(unsigned, b); }
; __device__ __forceinline__ float bf_lo(unsigned w) { return __uint_as_float(w << 16); }
; __device__ __forceinline__ float bf_hi(unsigned w) { return __uint_as_float(w & 0xffff0000u); }
;     __device__ __forceinline__ void operator()(f32x4 (&acc)[2][2][4][2], const Unit& u, int wr, int wc, int fr, int fq) const {
;     ...
;             for (int m = 0; m < 4; ++m)
; #pragma unroll
;                 for (int bj = 0; bj < 2; ++bj) {
;                     const u32x4 g = ga[m][bj];
;                     const f32x4 a0 = (f32x4){bf_lo(g.x), bf_hi(g.x), bf_lo(g.y), bf_hi(g.y)}, a1 = (f32x4){bf_lo(g.z), bf_hi(g.z), bf_lo(g.w), bf_hi(g.w)};
;                     acc[ai][bj][m][0] *= a0; acc[ai][bj][m][1] *= a1;
;                     if (u.seg != 0) {
;                         const f32x4 v0 = acc[ai][bj][m][0], v1 = acc[ai][bj][m][1];
;                         u32x4 w; w.x = cvt_pk_bf16(v0[0], v0[1]); w.y = cvt_pk_bf16(v0[2], v0[3]); w.z = cvt_pk_bf16(v1[0], v1[1]); w.w = cvt_pk_bf16(v1[2], v1[3]);
;                         *(u32x4*)(O + (size_t)(row0 + ai * HALF + m * 16) * 1024 + col0 + bj * HALF) = w;
;                     }
.LBB0_541:
	s_nop 0
	v_lshlrev_b32_e32 v154, 16, v148
	v_and_b32_e32 v155, 0xffff0000, v148
	v_lshlrev_b32_e32 v148, 16, v149
	v_and_b32_e32 v149, 0xffff0000, v149
	v_lshlrev_b32_e32 v156, 16, v150
	v_and_b32_e32 v157, 0xffff0000, v150
	v_lshlrev_b32_e32 v150, 16, v151
	v_and_b32_e32 v151, 0xffff0000, v151
	v_pk_mul_f32 v[24:25], v[24:25], v[148:149]
	v_pk_mul_f32 v[22:23], v[22:23], v[154:155]
	v_pk_mul_f32 v[20:21], v[20:21], v[150:151]
	s_and_b64 vcc, exec, s[38:39]
	v_pk_mul_f32 v[18:19], v[18:19], v[156:157]
	s_cbranch_vccnz .LBB0_543
	v_cvt_pk_bf16_f32 v148, v22, v23
	v_cvt_pk_bf16_f32 v149, v24, v25
	v_cvt_pk_bf16_f32 v150, v18, v19
	v_cvt_pk_bf16_f32 v151, v20, v21
	global_store_dwordx4 v[152:153], v[148:151], off offset:256
.LBB0_543:
	v_ashrrev_i32_e32 v183, 31, v182
	s_nop 0
	v_lshlrev_b64 v[148:149], 11, v[182:183]
	v_lshlrev_b32_e32 v150, 16, v144
	v_and_b32_e32 v151, 0xffff0000, v144
	v_lshlrev_b32_e32 v144, 16, v145
	v_and_b32_e32 v145, 0xffff0000, v145
	v_lshlrev_b32_e32 v152, 16, v146
	v_and_b32_e32 v153, 0xffff0000, v146
	v_lshlrev_b32_e32 v146, 16, v147
	v_and_b32_e32 v147, 0xffff0000, v147
	v_pk_mul_f32 v[48:49], v[48:49], v[144:145]
	v_lshl_add_u64 v[144:145], s[86:87], 0, v[148:149]
	v_pk_mul_f32 v[46:47], v[46:47], v[150:151]
	v_pk_mul_f32 v[44:45], v[44:45], v[146:147]
	v_pk_mul_f32 v[42:43], v[42:43], v[152:153]
	s_and_b64 vcc, exec, s[38:39]
	v_lshl_add_u64 v[144:145], v[176:177], 1, v[144:145]
	s_cbranch_vccnz .LBB0_545
	v_cvt_pk_bf16_f32 v146, v46, v47
	v_cvt_pk_bf16_f32 v147, v48, v49
	v_cvt_pk_bf16_f32 v148, v42, v43
	v_cvt_pk_bf16_f32 v149, v44, v45
	global_store_dwordx4 v[144:145], v[146:149], off
.LBB0_545:
	s_nop 0
	v_lshlrev_b32_e32 v146, 16, v140
	v_and_b32_e32 v147, 0xffff0000, v140
	v_lshlrev_b32_e32 v140, 16, v141
	v_and_b32_e32 v141, 0xffff0000, v141
	v_lshlrev_b32_e32 v148, 16, v142
	v_and_b32_e32 v149, 0xffff0000, v142
	v_lshlrev_b32_e32 v142, 16, v143
	v_and_b32_e32 v143, 0xffff0000, v143
	v_pk_mul_f32 v[16:17], v[16:17], v[140:141]
	v_pk_mul_f32 v[14:15], v[14:15], v[146:147]
	v_pk_mul_f32 v[12:13], v[12:13], v[142:143]
	s_and_b64 vcc, exec, s[38:39]
	v_pk_mul_f32 v[10:11], v[10:11], v[148:149]
	s_cbranch_vccnz .LBB0_547
	v_cvt_pk_bf16_f32 v140, v14, v15
	v_cvt_pk_bf16_f32 v141, v16, v17
	v_cvt_pk_bf16_f32 v142, v10, v11
	v_cvt_pk_bf16_f32 v143, v12, v13
	global_store_dwordx4 v[144:145], v[140:143], off offset:256
.LBB0_547:
	v_ashrrev_i32_e32 v179, 31, v178
	s_nop 0
	v_lshlrev_b64 v[140:141], 11, v[178:179]
	v_lshlrev_b32_e32 v142, 16, v136
	v_and_b32_e32 v143, 0xffff0000, v136
	v_lshlrev_b32_e32 v136, 16, v137
	v_and_b32_e32 v137, 0xffff0000, v137
	v_lshlrev_b32_e32 v144, 16, v138
	v_and_b32_e32 v145, 0xffff0000, v138
	v_lshlrev_b32_e32 v138, 16, v139
	v_and_b32_e32 v139, 0xffff0000, v139
	v_pk_mul_f32 v[40:41], v[40:41], v[136:137]
	v_lshl_add_u64 v[136:137], s[86:87], 0, v[140:141]
	v_pk_mul_f32 v[38:39], v[38:39], v[142:143]
	v_pk_mul_f32 v[36:37], v[36:37], v[138:139]
	v_pk_mul_f32 v[34:35], v[34:35], v[144:145]
	s_and_b64 vcc, exec, s[38:39]
	v_lshl_add_u64 v[136:137], v[176:177], 1, v[136:137]
	s_cbranch_vccnz .LBB0_549
	v_cvt_pk_bf16_f32 v138, v38, v39
	v_cvt_pk_bf16_f32 v139, v40, v41
	v_cvt_pk_bf16_f32 v140, v34, v35
	v_cvt_pk_bf16_f32 v141, v36, v37
	global_store_dwordx4 v[136:137], v[138:141], off
.LBB0_549:
	s_nop 0
	v_lshlrev_b32_e32 v138, 16, v132
	v_and_b32_e32 v139, 0xffff0000, v132
	v_lshlrev_b32_e32 v132, 16, v133
	v_and_b32_e32 v133, 0xffff0000, v133
	v_lshlrev_b32_e32 v140, 16, v134
	v_and_b32_e32 v141, 0xffff0000, v134
	v_lshlrev_b32_e32 v134, 16, v135
	v_and_b32_e32 v135, 0xffff0000, v135
	v_pk_mul_f32 v[8:9], v[8:9], v[132:133]
	v_pk_mul_f32 v[6:7], v[6:7], v[138:139]
	v_pk_mul_f32 v[4:5], v[4:5], v[134:135]
	s_and_b64 vcc, exec, s[38:39]
	v_pk_mul_f32 v[2:3], v[2:3], v[140:141]
	s_cbranch_vccnz .LBB0_551
	v_cvt_pk_bf16_f32 v132, v6, v7
	v_cvt_pk_bf16_f32 v133, v8, v9
	v_cvt_pk_bf16_f32 v134, v2, v3
	v_cvt_pk_bf16_f32 v135, v4, v5
	global_store_dwordx4 v[136:137], v[132:135], off offset:256

; #define PG8_STAGE(bufoff, gbase, voff) do { _Pragma("unroll") for (int _i = 0; _i < 2; ++_i) \
;         __builtin_amdgcn_global_load_lds((const unsigned*)((const char*)(gbase) + (voff)[_i]), (PG8_LAS unsigned*)(lds + (bufoff) + ldsw + _i * 8192), 16, 0, 0); } while (0)
; #define PG8_LDA(dst, b, h) do { _Pragma("unroll") for (int m = 0; m < 4; ++m) _Pragma("unroll") for (int k = 0; k < 2; ++k) dst[m][k] = *(const PG8_LAS bf16x8*)(lds + PG8_SA(b, h) + aoff + m * 2048 + k * 1024); } while (0)
; #define PG8_LDB(dst, b, h) do { _Pragma("unroll") for (int n = 0; n < 2; ++n) _Pragma("unroll") for (int k = 0; k < 2; ++k) dst[n][k] = *(const PG8_LAS bf16x8*)(lds + PG8_SB(b, h) + boff + n * 2048 + k * 1024); } while (0)
; #define PG8_MMA(ai, bj, At, Bt) do { __builtin_amdgcn_s_setprio(1); _Pragma("unroll") for (int m = 0; m < 4; ++m) _Pragma("unroll") for (int n = 0; n < 2; ++n) _Pragma("unroll") for (int k = 0; k < 2; ++k) \
;         acc[ai][bj][m][n] = __builtin_amdgcn_mfma_f32_16x16x32_bf16(Bt[n][k], At[m][k], acc[ai][bj][m][n], 0, 0, 0); __builtin_amdgcn_s_setprio(0); } while (0)
; #define PG8_WAIT_V(n) asm volatile("s_waitcnt vmcnt(" #n ")" ::: "memory")
; #define PG8_WAIT_L(n) asm volatile("s_waitcnt lgkmcnt(" #n ")" ::: "memory")
; #define PG8_BAR __builtin_amdgcn_s_barrier()
; #define PG8_SCHED __builtin_amdgcn_sched_barrier(0)
; template <class Epi, class Sched, bool ALIGN_EPI = false, bool SP2 = false>
; __device__ __forceinline__ void gemm_phase(PG8_LAS unsigned char* lds, const Gemm g, const Sched& S, const Epi& E) {
;     ...
;             PG8_LDB(B0, 0, 0); PG8_LDB(B1, 0, 1); PG8_SCHED; PG8_LDA(At, 0, 0); PG8_STAGE(PG8_SA(1, 1), a1 + hstep, voffA);
;             PG8_WAIT_V(8); PG8_WAIT_L(0); PG8_BAR; PG8_MMA(0, 0, At, B0); PG8_MMA(0, 1, At, B1); PG8_BAR; PG8_SCHED;
;             PG8_LDA(At, 0, 1); PG8_STAGE(PG8_SB(0, 0), b2, voffB); PG8_STAGE(PG8_SB(0, 1), b2 + hstepB, voffB); PG8_STAGE(PG8_SA(0, 0), a2, voffA);
;             PG8_WAIT_V(8); PG8_WAIT_L(0); PG8_BAR; PG8_MMA(1, 0, At, B0); PG8_MMA(1, 1, At, B1); PG8_BAR; PG8_SCHED;
.LBB0_646:
	s_add_u32 s35, s70, 0xfffc0080
	s_addc_u32 s72, s71, -1
	s_add_i32 s88, 0, 0x10000
	s_cmp_eq_u32 s34, 12
	s_cselect_b32 s75, s49, s72
	s_cselect_b32 s74, vcc_lo, s35
	s_cselect_b32 s73, s51, s31
	s_cselect_b32 s72, vcc_hi, s30
	s_add_i32 s35, 0, 0x14000
	v_add_u32_e32 v144, s88, v204
	v_add_u32_e32 v176, s35, v204
	ds_read_b128 v[132:135], v144
	ds_read_b128 v[136:139], v144 offset:1024
	ds_read_b128 v[140:143], v144 offset:2048
	ds_read_b128 v[144:147], v144 offset:3072
	ds_read_b128 v[148:151], v176
	ds_read_b128 v[152:155], v176 offset:1024
	ds_read_b128 v[156:159], v176 offset:2048
	ds_read_b128 v[176:179], v176 offset:3072
	v_lshl_add_u64 v[192:193], s[70:71], 0, v[172:173]
	s_add_i32 m0, s77, 0xc000
	ds_read_b128 v[180:183], v206
	ds_read_b128 v[184:187], v206 offset:1024
	ds_read_b128 v[188:191], v206 offset:2048
	ds_read_b128 v[208:211], v206 offset:3072
	ds_read_b128 v[212:215], v206 offset:4096
	ds_read_b128 v[216:219], v206 offset:5120
	ds_read_b128 v[220:223], v206 offset:6144
	ds_read_b128 v[224:227], v206 offset:7168
	global_load_lds_dwordx4 v[192:193], off
	v_lshl_add_u64 v[192:193], s[70:71], 0, v[174:175]
	s_add_i32 m0, s77, 0xe000
	s_nop 0
	global_load_lds_dwordx4 v[192:193], off
	s_waitcnt vmcnt(8)
	s_waitcnt lgkmcnt(0)
	s_barrier
	s_setprio 1
	s_waitcnt lgkmcnt(0)
	v_mfma_f32_16x16x32_bf16 v[128:131], v[132:135], v[180:183], v[128:131]
	v_mfma_f32_16x16x32_bf16 v[124:127], v[140:143], v[180:183], v[124:127]
	v_mfma_f32_16x16x32_bf16 v[112:115], v[132:135], v[188:191], v[112:115]
	v_mfma_f32_16x16x32_bf16 v[108:111], v[140:143], v[188:191], v[108:111]
	v_mfma_f32_16x16x32_bf16 v[96:99], v[132:135], v[212:215], v[96:99]
	v_mfma_f32_16x16x32_bf16 v[92:95], v[140:143], v[212:215], v[92:95]
	v_mfma_f32_16x16x32_bf16 v[80:83], v[132:135], v[220:223], v[80:83]
	v_mfma_f32_16x16x32_bf16 v[76:79], v[140:143], v[220:223], v[76:79]
	v_mfma_f32_16x16x32_bf16 v[128:131], v[136:139], v[184:187], v[128:131]
	v_mfma_f32_16x16x32_bf16 v[124:127], v[144:147], v[184:187], v[124:127]
	v_mfma_f32_16x16x32_bf16 v[112:115], v[136:139], v[208:211], v[112:115]
	v_mfma_f32_16x16x32_bf16 v[108:111], v[144:147], v[208:211], v[108:111]
	v_mfma_f32_16x16x32_bf16 v[96:99], v[136:139], v[216:219], v[96:99]
	v_mfma_f32_16x16x32_bf16 v[92:95], v[144:147], v[216:219], v[92:95]
	v_mfma_f32_16x16x32_bf16 v[80:83], v[136:139], v[224:227], v[80:83]
	v_mfma_f32_16x16x32_bf16 v[76:79], v[144:147], v[224:227], v[76:79]
	s_setprio 0
	s_setprio 1
	v_mfma_f32_16x16x32_bf16 v[120:123], v[148:151], v[180:183], v[120:123]
	v_mfma_f32_16x16x32_bf16 v[116:119], v[156:159], v[180:183], v[116:119]
	v_mfma_f32_16x16x32_bf16 v[104:107], v[148:151], v[188:191], v[104:107]
	v_mfma_f32_16x16x32_bf16 v[100:103], v[156:159], v[188:191], v[100:103]
	v_mfma_f32_16x16x32_bf16 v[88:91], v[148:151], v[212:215], v[88:91]
	v_mfma_f32_16x16x32_bf16 v[84:87], v[156:159], v[212:215], v[84:87]
	v_mfma_f32_16x16x32_bf16 v[72:75], v[148:151], v[220:223], v[72:75]
	v_mfma_f32_16x16x32_bf16 v[68:71], v[156:159], v[220:223], v[68:71]
	v_mfma_f32_16x16x32_bf16 v[120:123], v[152:155], v[184:187], v[120:123]
	v_mfma_f32_16x16x32_bf16 v[116:119], v[176:179], v[184:187], v[116:119]
	v_mfma_f32_16x16x32_bf16 v[104:107], v[152:155], v[208:211], v[104:107]
	v_mfma_f32_16x16x32_bf16 v[100:103], v[176:179], v[208:211], v[100:103]
	v_mfma_f32_16x16x32_bf16 v[88:91], v[152:155], v[216:219], v[88:91]
	v_mfma_f32_16x16x32_bf16 v[84:87], v[176:179], v[216:219], v[84:87]
	v_mfma_f32_16x16x32_bf16 v[72:75], v[152:155], v[224:227], v[72:75]
	v_mfma_f32_16x16x32_bf16 v[68:71], v[176:179], v[224:227], v[68:71]
	s_setprio 0
	s_barrier
	s_add_i32 s88, s88, s76
	v_lshl_add_u64 v[192:193], s[72:73], 0, v[168:169]
	s_mov_b32 m0, s88
	ds_read_b128 v[180:183], v206 offset:16384
	ds_read_b128 v[184:187], v206 offset:17408
	ds_read_b128 v[188:191], v206 offset:18432
	ds_read_b128 v[208:211], v206 offset:19456
	ds_read_b128 v[212:215], v206 offset:20480
	ds_read_b128 v[216:219], v206 offset:21504
	ds_read_b128 v[220:223], v206 offset:22528
	ds_read_b128 v[224:227], v206 offset:23552
	global_load_lds_dwordx4 v[192:193], off
	s_add_i32 m0, s88, 0x2000
	s_add_u32 s88, s72, 0x40000
	v_lshl_add_u64 v[228:229], s[72:73], 0, v[164:165]
	s_addc_u32 s89, s73, 0
	s_add_i32 s35, s35, s76
	global_load_lds_dwordx4 v[228:229], off
	v_lshl_add_u64 v[230:231], s[88:89], 0, v[168:169]
	s_mov_b32 m0, s35
	v_lshl_add_u64 v[232:233], s[74:75], 0, v[166:167]
	global_load_lds_dwordx4 v[230:231], off
	v_lshl_add_u64 v[230:231], s[88:89], 0, v[164:165]
	s_add_i32 m0, s35, 0x2000
	s_nop 0
	global_load_lds_dwordx4 v[230:231], off
	v_lshl_add_u64 v[230:231], s[74:75], 0, v[170:171]
	s_mov_b32 m0, s77
	s_nop 0
	global_load_lds_dwordx4 v[230:231], off
	s_mov_b32 m0, s36
	s_nop 0
	global_load_lds_dwordx4 v[232:233], off
	s_waitcnt vmcnt(8)
	s_waitcnt lgkmcnt(0)
	s_barrier
; #define PG8_STAGE(bufoff, gbase, voff) do { _Pragma("unroll") for (int _i = 0; _i < 2; ++_i) \
;         __builtin_amdgcn_global_load_lds((const unsigned*)((const char*)(gbase) + (voff)[_i]), (PG8_LAS unsigned*)(lds + (bufoff) + ldsw + _i * 8192), 16, 0, 0); } while (0)
; #define PG8_LDA(dst, b, h) do { _Pragma("unroll") for (int m = 0; m < 4; ++m) _Pragma("unroll") for (int k = 0; k < 2; ++k) dst[m][k] = *(const PG8_LAS bf16x8*)(lds + PG8_SA(b, h) + aoff + m * 2048 + k * 1024); } while (0)
; #define PG8_LDB(dst, b, h) do { _Pragma("unroll") for (int n = 0; n < 2; ++n) _Pragma("unroll") for (int k = 0; k < 2; ++k) dst[n][k] = *(const PG8_LAS bf16x8*)(lds + PG8_SB(b, h) + boff + n * 2048 + k * 1024); } while (0)
; #define PG8_MMA(ai, bj, At, Bt) do { __builtin_amdgcn_s_setprio(1); _Pragma("unroll") for (int m = 0; m < 4; ++m) _Pragma("unroll") for (int n = 0; n < 2; ++n) _Pragma("unroll") for (int k = 0; k < 2; ++k) \
;         acc[ai][bj][m][n] = __builtin_amdgcn_mfma_f32_16x16x32_bf16(Bt[n][k], At[m][k], acc[ai][bj][m][n], 0, 0, 0); __builtin_amdgcn_s_setprio(0); } while (0)
; #define PG8_WAIT_V(n) asm volatile("s_waitcnt vmcnt(" #n ")" ::: "memory")
; #define PG8_WAIT_L(n) asm volatile("s_waitcnt lgkmcnt(" #n ")" ::: "memory")
; #define PG8_BAR __builtin_amdgcn_s_barrier()
; #define PG8_SCHED __builtin_amdgcn_sched_barrier(0)
; template <class Epi, class Sched, bool ALIGN_EPI = false, bool SP2 = false>
; __device__ __forceinline__ void gemm_phase(PG8_LAS unsigned char* lds, const Gemm g, const Sched& S, const Epi& E) {
;     ...
;             PG8_WAIT_V(8); PG8_WAIT_L(0); PG8_BAR; PG8_MMA(1, 0, At, B0); PG8_MMA(1, 1, At, B1); PG8_BAR; PG8_SCHED;
;             PG8_LDB(B0, 1, 0); PG8_LDB(B1, 1, 1); PG8_SCHED; PG8_LDA(At, 1, 0); PG8_STAGE(PG8_SA(0, 1), a2 + hstep, voffA);
;             PG8_WAIT_V(8); PG8_WAIT_L(0); PG8_BAR; PG8_MMA(0, 0, At, B0); PG8_MMA(0, 1, At, B1); PG8_BAR; PG8_SCHED;
	s_setprio 1
	s_waitcnt lgkmcnt(0)
	v_mfma_f32_16x16x32_bf16 v[62:65], v[132:135], v[180:183], v[62:65]
	v_mfma_f32_16x16x32_bf16 v[58:61], v[140:143], v[180:183], v[58:61]
	v_mfma_f32_16x16x32_bf16 v[46:49], v[132:135], v[188:191], v[46:49]
	v_mfma_f32_16x16x32_bf16 v[42:45], v[140:143], v[188:191], v[42:45]
	v_mfma_f32_16x16x32_bf16 v[30:33], v[132:135], v[212:215], v[30:33]
	v_mfma_f32_16x16x32_bf16 v[26:29], v[140:143], v[212:215], v[26:29]
	v_mfma_f32_16x16x32_bf16 v[14:17], v[132:135], v[220:223], v[14:17]
	v_mfma_f32_16x16x32_bf16 v[10:13], v[140:143], v[220:223], v[10:13]
	v_mfma_f32_16x16x32_bf16 v[62:65], v[136:139], v[184:187], v[62:65]
	v_mfma_f32_16x16x32_bf16 v[58:61], v[144:147], v[184:187], v[58:61]
	v_mfma_f32_16x16x32_bf16 v[46:49], v[136:139], v[208:211], v[46:49]
	v_mfma_f32_16x16x32_bf16 v[42:45], v[144:147], v[208:211], v[42:45]
	v_mfma_f32_16x16x32_bf16 v[30:33], v[136:139], v[216:219], v[30:33]
	v_mfma_f32_16x16x32_bf16 v[26:29], v[144:147], v[216:219], v[26:29]
	v_mfma_f32_16x16x32_bf16 v[14:17], v[136:139], v[224:227], v[14:17]
	v_mfma_f32_16x16x32_bf16 v[10:13], v[144:147], v[224:227], v[10:13]
	s_setprio 0
	s_setprio 1
	v_mfma_f32_16x16x32_bf16 v[54:57], v[148:151], v[180:183], v[54:57]
	v_mfma_f32_16x16x32_bf16 v[50:53], v[156:159], v[180:183], v[50:53]
	v_mfma_f32_16x16x32_bf16 v[38:41], v[148:151], v[188:191], v[38:41]
	v_mfma_f32_16x16x32_bf16 v[34:37], v[156:159], v[188:191], v[34:37]
	v_mfma_f32_16x16x32_bf16 v[22:25], v[148:151], v[212:215], v[22:25]
	v_mfma_f32_16x16x32_bf16 v[18:21], v[156:159], v[212:215], v[18:21]
	v_mfma_f32_16x16x32_bf16 v[6:9], v[148:151], v[220:223], v[6:9]
	v_mfma_f32_16x16x32_bf16 v[2:5], v[156:159], v[220:223], v[2:5]
	v_mfma_f32_16x16x32_bf16 v[54:57], v[152:155], v[184:187], v[54:57]
	v_mfma_f32_16x16x32_bf16 v[50:53], v[176:179], v[184:187], v[50:53]
	v_mfma_f32_16x16x32_bf16 v[38:41], v[152:155], v[208:211], v[38:41]
	v_mfma_f32_16x16x32_bf16 v[34:37], v[176:179], v[208:211], v[34:37]
	v_mfma_f32_16x16x32_bf16 v[22:25], v[152:155], v[216:219], v[22:25]
	v_mfma_f32_16x16x32_bf16 v[18:21], v[176:179], v[216:219], v[18:21]
	v_mfma_f32_16x16x32_bf16 v[6:9], v[152:155], v[224:227], v[6:9]
	v_mfma_f32_16x16x32_bf16 v[2:5], v[176:179], v[224:227], v[2:5]
	s_setprio 0
	s_barrier
	s_add_i32 s35, 0, 0x18000
	s_add_i32 s88, 0, 0x1c000
	v_add_u32_e32 v144, s35, v204
	v_add_u32_e32 v176, s88, v204
	ds_read_b128 v[132:135], v144
	ds_read_b128 v[136:139], v144 offset:1024
	ds_read_b128 v[140:143], v144 offset:2048
	ds_read_b128 v[144:147], v144 offset:3072
	ds_read_b128 v[148:151], v176
	ds_read_b128 v[152:155], v176 offset:1024
	ds_read_b128 v[156:159], v176 offset:2048
	ds_read_b128 v[176:179], v176 offset:3072
	s_add_u32 s74, s74, 0x40000
	s_addc_u32 s75, s75, 0
	s_mov_b32 m0, s37
	v_lshl_add_u64 v[234:235], s[74:75], 0, v[170:171]
	ds_read_b128 v[180:183], v206 offset:32768
	ds_read_b128 v[184:187], v206 offset:33792
	ds_read_b128 v[188:191], v206 offset:34816
	ds_read_b128 v[208:211], v206 offset:35840
	ds_read_b128 v[212:215], v206 offset:36864
	ds_read_b128 v[216:219], v206 offset:37888
	ds_read_b128 v[220:223], v206 offset:38912
	ds_read_b128 v[224:227], v206 offset:39936
	global_load_lds_dwordx4 v[234:235], off
	v_lshl_add_u64 v[234:235], s[74:75], 0, v[166:167]
	s_mov_b32 m0, s23
	s_nop 0
	global_load_lds_dwordx4 v[234:235], off
	s_waitcnt vmcnt(8)
	s_waitcnt lgkmcnt(0)
	s_barrier
	s_setprio 1
	s_waitcnt lgkmcnt(0)
	v_mfma_f32_16x16x32_bf16 v[128:131], v[132:135], v[180:183], v[128:131]
	v_mfma_f32_16x16x32_bf16 v[124:127], v[140:143], v[180:183], v[124:127]
	v_mfma_f32_16x16x32_bf16 v[112:115], v[132:135], v[188:191], v[112:115]
	v_mfma_f32_16x16x32_bf16 v[108:111], v[140:143], v[188:191], v[108:111]
	v_mfma_f32_16x16x32_bf16 v[96:99], v[132:135], v[212:215], v[96:99]
	v_mfma_f32_16x16x32_bf16 v[92:95], v[140:143], v[212:215], v[92:95]
	v_mfma_f32_16x16x32_bf16 v[80:83], v[132:135], v[220:223], v[80:83]
	v_mfma_f32_16x16x32_bf16 v[76:79], v[140:143], v[220:223], v[76:79]
	v_mfma_f32_16x16x32_bf16 v[128:131], v[136:139], v[184:187], v[128:131]
	v_mfma_f32_16x16x32_bf16 v[124:127], v[144:147], v[184:187], v[124:127]
	v_mfma_f32_16x16x32_bf16 v[112:115], v[136:139], v[208:211], v[112:115]
	v_mfma_f32_16x16x32_bf16 v[108:111], v[144:147], v[208:211], v[108:111]
	v_mfma_f32_16x16x32_bf16 v[96:99], v[136:139], v[216:219], v[96:99]
	v_mfma_f32_16x16x32_bf16 v[92:95], v[144:147], v[216:219], v[92:95]
	v_mfma_f32_16x16x32_bf16 v[80:83], v[136:139], v[224:227], v[80:83]
	v_mfma_f32_16x16x32_bf16 v[76:79], v[144:147], v[224:227], v[76:79]
	s_setprio 0
	s_setprio 1
	v_mfma_f32_16x16x32_bf16 v[120:123], v[148:151], v[180:183], v[120:123]
	v_mfma_f32_16x16x32_bf16 v[116:119], v[156:159], v[180:183], v[116:119]
	v_mfma_f32_16x16x32_bf16 v[104:107], v[148:151], v[188:191], v[104:107]
	v_mfma_f32_16x16x32_bf16 v[100:103], v[156:159], v[188:191], v[100:103]
	v_mfma_f32_16x16x32_bf16 v[88:91], v[148:151], v[212:215], v[88:91]
	v_mfma_f32_16x16x32_bf16 v[84:87], v[156:159], v[212:215], v[84:87]
	v_mfma_f32_16x16x32_bf16 v[72:75], v[148:151], v[220:223], v[72:75]
	v_mfma_f32_16x16x32_bf16 v[68:71], v[156:159], v[220:223], v[68:71]
	v_mfma_f32_16x16x32_bf16 v[120:123], v[152:155], v[184:187], v[120:123]
	v_mfma_f32_16x16x32_bf16 v[116:119], v[176:179], v[184:187], v[116:119]
	v_mfma_f32_16x16x32_bf16 v[104:107], v[152:155], v[208:211], v[104:107]
	v_mfma_f32_16x16x32_bf16 v[100:103], v[176:179], v[208:211], v[100:103]
	v_mfma_f32_16x16x32_bf16 v[88:91], v[152:155], v[216:219], v[88:91]
	v_mfma_f32_16x16x32_bf16 v[84:87], v[176:179], v[216:219], v[84:87]
	v_mfma_f32_16x16x32_bf16 v[72:75], v[152:155], v[224:227], v[72:75]
	v_mfma_f32_16x16x32_bf16 v[68:71], v[176:179], v[224:227], v[68:71]
	s_setprio 0
	s_barrier
; #define PG8_STAGE(bufoff, gbase, voff) do { _Pragma("unroll") for (int _i = 0; _i < 2; ++_i) \
;         __builtin_amdgcn_global_load_lds((const unsigned*)((const char*)(gbase) + (voff)[_i]), (PG8_LAS unsigned*)(lds + (bufoff) + ldsw + _i * 8192), 16, 0, 0); } while (0)
; #define PG8_LDA(dst, b, h) do { _Pragma("unroll") for (int m = 0; m < 4; ++m) _Pragma("unroll") for (int k = 0; k < 2; ++k) dst[m][k] = *(const PG8_LAS bf16x8*)(lds + PG8_SA(b, h) + aoff + m * 2048 + k * 1024); } while (0)
; #define PG8_MMA(ai, bj, At, Bt) do { __builtin_amdgcn_s_setprio(1); _Pragma("unroll") for (int m = 0; m < 4; ++m) _Pragma("unroll") for (int n = 0; n < 2; ++n) _Pragma("unroll") for (int k = 0; k < 2; ++k) \
;         acc[ai][bj][m][n] = __builtin_amdgcn_mfma_f32_16x16x32_bf16(Bt[n][k], At[m][k], acc[ai][bj][m][n], 0, 0, 0); __builtin_amdgcn_s_setprio(0); } while (0)
; #define PG8_WAIT_V(n) asm volatile("s_waitcnt vmcnt(" #n ")" ::: "memory")
; #define PG8_WAIT_L(n) asm volatile("s_waitcnt lgkmcnt(" #n ")" ::: "memory")
; #define PG8_BAR __builtin_amdgcn_s_barrier()
; #define PG8_SCHED __builtin_amdgcn_sched_barrier(0)
; template <class Epi, class Sched, bool ALIGN_EPI = false, bool SP2 = false>
; __device__ __forceinline__ void gemm_phase(PG8_LAS unsigned char* lds, const Gemm g, const Sched& S, const Epi& E) {
;     ...
;             PG8_WAIT_V(8); PG8_WAIT_L(0); PG8_BAR; PG8_MMA(0, 0, At, B0); PG8_MMA(0, 1, At, B1); PG8_BAR; PG8_SCHED;
;             PG8_LDA(At, 1, 1); PG8_STAGE(PG8_SB(1, 0), b3, voffB); PG8_STAGE(PG8_SB(1, 1), b3 + hstepB, voffB); PG8_STAGE(PG8_SA(1, 0), a3, voffA);
;             PG8_WAIT_V(8); PG8_WAIT_L(0); PG8_BAR; PG8_MMA(1, 0, At, B0); PG8_MMA(1, 1, At, B1); PG8_BAR; PG8_SCHED;
	s_add_i32 s35, s35, s76
	v_lshl_add_u64 v[192:193], v[192:193], 0, s[52:53]
	s_mov_b32 m0, s35
	ds_read_b128 v[180:183], v206 offset:49152
	ds_read_b128 v[184:187], v206 offset:50176
	ds_read_b128 v[188:191], v206 offset:51200
	ds_read_b128 v[208:211], v206 offset:52224
	ds_read_b128 v[212:215], v206 offset:53248
	ds_read_b128 v[216:219], v206 offset:54272
	ds_read_b128 v[220:223], v206 offset:55296
	ds_read_b128 v[224:227], v206 offset:56320
	global_load_lds_dwordx4 v[192:193], off
	s_add_i32 m0, s35, 0x2000
	s_add_u32 s72, s72, 0x40080
	v_lshl_add_u64 v[192:193], v[228:229], 0, s[52:53]
	s_addc_u32 s73, s73, 0
	s_add_i32 s35, s88, s76
	global_load_lds_dwordx4 v[192:193], off
	v_lshl_add_u64 v[192:193], s[72:73], 0, v[168:169]
	s_mov_b32 m0, s35
	s_nop 0
	global_load_lds_dwordx4 v[192:193], off
	v_lshl_add_u64 v[192:193], s[72:73], 0, v[164:165]
	s_add_i32 m0, s35, 0x2000
	s_nop 0
	global_load_lds_dwordx4 v[192:193], off
	v_lshl_add_u64 v[192:193], v[230:231], 0, s[52:53]
	s_mov_b32 m0, s26
	s_nop 0
	global_load_lds_dwordx4 v[192:193], off
	v_lshl_add_u64 v[192:193], v[232:233], 0, s[52:53]
	s_mov_b32 m0, s27
	s_nop 0
	global_load_lds_dwordx4 v[192:193], off
	s_waitcnt vmcnt(8)
	s_waitcnt lgkmcnt(0)
	s_barrier
	s_setprio 1
	s_waitcnt lgkmcnt(0)
	v_mfma_f32_16x16x32_bf16 v[62:65], v[132:135], v[180:183], v[62:65]
	v_mfma_f32_16x16x32_bf16 v[58:61], v[140:143], v[180:183], v[58:61]
	v_mfma_f32_16x16x32_bf16 v[46:49], v[132:135], v[188:191], v[46:49]
	v_mfma_f32_16x16x32_bf16 v[42:45], v[140:143], v[188:191], v[42:45]
	v_mfma_f32_16x16x32_bf16 v[30:33], v[132:135], v[212:215], v[30:33]
	v_mfma_f32_16x16x32_bf16 v[26:29], v[140:143], v[212:215], v[26:29]
	v_mfma_f32_16x16x32_bf16 v[14:17], v[132:135], v[220:223], v[14:17]
	v_mfma_f32_16x16x32_bf16 v[10:13], v[140:143], v[220:223], v[10:13]
	v_mfma_f32_16x16x32_bf16 v[62:65], v[136:139], v[184:187], v[62:65]
	v_mfma_f32_16x16x32_bf16 v[58:61], v[144:147], v[184:187], v[58:61]
	v_mfma_f32_16x16x32_bf16 v[46:49], v[136:139], v[208:211], v[46:49]
	v_mfma_f32_16x16x32_bf16 v[42:45], v[144:147], v[208:211], v[42:45]
	v_mfma_f32_16x16x32_bf16 v[30:33], v[136:139], v[216:219], v[30:33]
	v_mfma_f32_16x16x32_bf16 v[26:29], v[144:147], v[216:219], v[26:29]
	v_mfma_f32_16x16x32_bf16 v[14:17], v[136:139], v[224:227], v[14:17]
	v_mfma_f32_16x16x32_bf16 v[10:13], v[144:147], v[224:227], v[10:13]
	s_setprio 0
	s_setprio 1
	v_mfma_f32_16x16x32_bf16 v[54:57], v[148:151], v[180:183], v[54:57]
	v_mfma_f32_16x16x32_bf16 v[50:53], v[156:159], v[180:183], v[50:53]
	v_mfma_f32_16x16x32_bf16 v[38:41], v[148:151], v[188:191], v[38:41]
	v_mfma_f32_16x16x32_bf16 v[34:37], v[156:159], v[188:191], v[34:37]
	v_mfma_f32_16x16x32_bf16 v[22:25], v[148:151], v[212:215], v[22:25]
	v_mfma_f32_16x16x32_bf16 v[18:21], v[156:159], v[212:215], v[18:21]
	v_mfma_f32_16x16x32_bf16 v[6:9], v[148:151], v[220:223], v[6:9]
	v_mfma_f32_16x16x32_bf16 v[2:5], v[156:159], v[220:223], v[2:5]
	v_mfma_f32_16x16x32_bf16 v[54:57], v[152:155], v[184:187], v[54:57]
	v_mfma_f32_16x16x32_bf16 v[50:53], v[176:179], v[184:187], v[50:53]
	v_mfma_f32_16x16x32_bf16 v[38:41], v[152:155], v[208:211], v[38:41]
	v_mfma_f32_16x16x32_bf16 v[34:37], v[176:179], v[208:211], v[34:37]
	v_mfma_f32_16x16x32_bf16 v[22:25], v[152:155], v[216:219], v[22:25]
	v_mfma_f32_16x16x32_bf16 v[18:21], v[176:179], v[216:219], v[18:21]
	v_mfma_f32_16x16x32_bf16 v[6:9], v[152:155], v[224:227], v[6:9]
	v_mfma_f32_16x16x32_bf16 v[2:5], v[176:179], v[224:227], v[2:5]
	s_setprio 0
	s_barrier
	s_add_i32 s34, s34, 2
	s_add_u32 s70, s70, 0x100
	s_addc_u32 s71, s71, 0
	s_add_u32 s30, s30, 0x100
	s_addc_u32 s31, s31, 0
	s_cmp_gt_u32 s34, 13
	s_cbranch_scc0 .LBB0_646
; __device__ __forceinline__ unsigned cvt_pk_bf16(float lo, float hi) { f32x2c v = {lo, hi}; bf16x2c b = __builtin_convertvector(v, bf16x2c); return __builtin_bit_cast(unsigned, b); }
; __device__ __forceinline__ float bf_lo(unsigned w) { return __uint_as_float(w << 16); }
; __device__ __forceinline__ float bf_hi(unsigned w) { return __uint_as_float(w & 0xffff0000u); }
;     __device__ __forceinline__ void operator()(f32x4 (&acc)[2][2][4][2], const Unit& u, int wr, int wc, int fr, int fq) const {
;         const int row0 = u.pm * BM + wr * 64 + fr, col0 = u.pn * BM + wc * 32 + 8 * fq;
; #pragma unroll
;         for (int ai = 0; ai < 2; ++ai) {
;             u32x4 bb[4][2];
; #pragma unroll
;             for (int m = 0; m < 4; ++m)
; #pragma unroll
;                 for (int bj = 0; bj < 2; ++bj) bb[m][bj] = *(const u32x4*)(baseh + (size_t)(row0 + ai * HALF + m * 16) * 1024 + col0 + bj * HALF);
; #pragma unroll
;             for (int m = 0; m < 4; ++m) {
;                 const int row = row0 + ai * HALF + m * 16; float s = 0.f;
; #pragma unroll
;                 for (int bj = 0; bj < 2; ++bj) {
;                     const u32x4 b = bb[m][bj];
;                     const f32x4 v0 = acc[ai][bj][m][0] + (f32x4){bf_lo(b.x), bf_hi(b.x), bf_lo(b.y), bf_hi(b.y)}, v1 = acc[ai][bj][m][1] + (f32x4){bf_lo(b.z), bf_hi(b.z), bf_lo(b.w), bf_hi(b.w)};
;                     s += (v0[0] * v0[0] + v0[1] * v0[1]) + (v0[2] * v0[2] + v0[3] * v0[3]) + (v1[0] * v1[0] + v1[1] * v1[1]) + (v1[2] * v1[2] + v1[3] * v1[3]);
;                     u32x4 w; w.x = cvt_pk_bf16(v0[0], v0[1]); w.y = cvt_pk_bf16(v0[2], v0[3]); w.z = cvt_pk_bf16(v1[0], v1[1]); w.w = cvt_pk_bf16(v1[2], v1[3]);
;                     *(u32x4*)(outh + (size_t)row * 1024 + col0 + bj * HALF) = w;
;                 }
;                 s += __shfl_xor(s, 16); s += __shfl_xor(s, 32);
;                 if (fq == 0) ssq[(size_t)(row >> 8) * pstride + (row & 255) * 16 + u.pn * 4 + wc] = s;
	v_and_b32_e32 v133, 64, v203
	v_xor_b32_e32 v132, 16, v203
	v_add_u32_e32 v133, 64, v133
	s_lshl_b32 s30, s84, 8
	v_cmp_lt_i32_e32 vcc, v132, v133
	s_add_i32 s30, s30, s25
	v_lshl_or_b32 v176, s29, 8, v205
	v_cndmask_b32_e32 v132, v203, v132, vcc
	v_or_b32_e32 v178, s30, v67
	v_ashrrev_i32_e32 v177, 31, v176
	v_lshlrev_b32_e32 v208, 2, v132
	v_xor_b32_e32 v132, 32, v203
	v_cmp_lt_i32_e32 vcc, v132, v133
	v_lshlrev_b64 v[214:215], 1, v[176:177]
	v_ashrrev_i32_e32 v179, 31, v178
	v_cndmask_b32_e32 v132, v203, v132, vcc
	v_lshl_add_u64 v[180:181], s[90:91], 0, v[214:215]
	v_lshlrev_b64 v[216:217], 11, v[178:179]
	v_lshlrev_b32_e32 v207, 2, v132
	v_lshl_add_u64 v[132:133], v[180:181], 0, v[216:217]
	global_load_dwordx4 v[210:213], v[132:133], off
	global_load_dwordx4 v[156:159], v[132:133], off offset:256
	v_or_b32_e32 v190, 16, v178
	v_ashrrev_i32_e32 v191, 31, v190
	v_or_b32_e32 v186, 32, v178
	v_lshlrev_b64 v[192:193], 11, v[190:191]
	v_ashrrev_i32_e32 v187, 31, v186
	v_or_b32_e32 v182, 48, v178
	v_lshl_add_u64 v[132:133], v[180:181], 0, v[192:193]
	v_lshlrev_b64 v[188:189], 11, v[186:187]
	v_ashrrev_i32_e32 v183, 31, v182
	global_load_dwordx4 v[152:155], v[132:133], off
	global_load_dwordx4 v[148:151], v[132:133], off offset:256
	v_lshl_add_u64 v[132:133], v[180:181], 0, v[188:189]
	v_lshlrev_b64 v[184:185], 11, v[182:183]
	global_load_dwordx4 v[144:147], v[132:133], off
	global_load_dwordx4 v[140:143], v[132:133], off offset:256
	v_lshl_add_u64 v[132:133], v[180:181], 0, v[184:185]
	global_load_dwordx4 v[136:139], v[132:133], off
	s_nop 0
	global_load_dwordx4 v[132:135], v[132:133], off offset:256
	v_lshlrev_b32_e32 v209, 4, v0
	v_add_u32_e32 v209, 0x21800, v209
	ds_write_b128 v209, v[172:175]
	s_mov_b64 s[100:101], 0x40000
	v_lshl_add_u64 v[236:237], v[180:181], 0, v[216:217]
	v_lshl_add_u64 v[236:237], v[236:237], 0, s[100:101]
	global_load_dwordx4 v[220:223], v[236:237], off
	global_load_dwordx4 v[224:227], v[236:237], off offset:256
	v_lshl_add_u64 v[236:237], v[180:181], 0, v[192:193]
	v_lshl_add_u64 v[236:237], v[236:237], 0, s[100:101]
	global_load_dwordx4 v[228:231], v[236:237], off
	global_load_dwordx4 v[232:235], v[236:237], off offset:256
	v_lshl_add_u64 v[236:237], v[180:181], 0, v[188:189]
	v_lshl_add_u64 v[236:237], v[236:237], 0, s[100:101]
	global_load_dwordx4 v[244:247], v[236:237], off
	global_load_dwordx4 v[248:251], v[236:237], off offset:256
	v_lshl_add_u64 v[236:237], v[180:181], 0, v[184:185]
	v_lshl_add_u64 v[236:237], v[236:237], 0, s[100:101]
	global_load_dwordx4 v[252:255], v[236:237], off
	global_load_dwordx4 v[172:175], v[236:237], off offset:256
	s_lshl_b32 s70, s29, 2
	s_ashr_i32 s72, s30, 8
	s_ashr_i32 s71, s70, 31
	s_ashr_i32 s73, s72, 31
	s_waitcnt vmcnt(8)
	v_lshlrev_b32_e32 v218, 16, v210
	v_and_b32_e32 v219, 0xffff0000, v210
	v_lshlrev_b32_e32 v210, 16, v211
	v_and_b32_e32 v211, 0xffff0000, v211
	v_pk_add_f32 v[130:131], v[130:131], v[210:211]
	v_pk_add_f32 v[128:129], v[128:129], v[218:219]
	v_lshlrev_b32_e32 v210, 16, v212
	v_and_b32_e32 v211, 0xffff0000, v212
	v_lshlrev_b32_e32 v212, 16, v213
	v_and_b32_e32 v213, 0xffff0000, v213
	v_pk_add_f32 v[212:213], v[126:127], v[212:213]
	v_mul_f32_e32 v126, v129, v129
	v_mul_f32_e32 v127, v131, v131
	v_pk_add_f32 v[124:125], v[124:125], v[210:211]
	v_fmac_f32_e32 v126, v128, v128
	v_fmac_f32_e32 v127, v130, v130
	v_add_f32_e32 v126, v126, v127
	v_mul_f32_e32 v127, v125, v125
	v_fmac_f32_e32 v127, v124, v124
	v_add_f32_e32 v126, v127, v126
	v_mul_f32_e32 v127, v213, v213
	v_fmac_f32_e32 v127, v212, v212
	v_add_f32_e32 v179, v127, v126
	v_cvt_pk_bf16_f32 v126, v128, v129
	v_cvt_pk_bf16_f32 v128, v124, v125
	v_lshl_add_u64 v[124:125], s[90:91], 0, v[216:217]
	v_cvt_pk_bf16_f32 v127, v130, v131
	v_cvt_pk_bf16_f32 v129, v212, v213
	v_lshl_add_u64 v[124:125], v[124:125], 0, v[214:215]
	global_store_dwordx4 v[124:125], v[126:129], off
	s_nop 1
	v_lshlrev_b32_e32 v126, 16, v156
	v_and_b32_e32 v127, 0xffff0000, v156
	v_lshlrev_b32_e32 v128, 16, v157
	v_and_b32_e32 v129, 0xffff0000, v157
	v_pk_add_f32 v[122:123], v[122:123], v[128:129]
	v_pk_add_f32 v[120:121], v[120:121], v[126:127]
	v_lshlrev_b32_e32 v126, 16, v158
	v_and_b32_e32 v127, 0xffff0000, v158
	v_lshlrev_b32_e32 v128, 16, v159
	v_and_b32_e32 v129, 0xffff0000, v159
	v_pk_add_f32 v[128:129], v[118:119], v[128:129]
	v_pk_add_f32 v[118:119], v[116:117], v[126:127]
	v_mul_f32_e32 v116, v121, v121
	v_mul_f32_e32 v117, v123, v123
	v_fmac_f32_e32 v116, v120, v120
	v_fmac_f32_e32 v117, v122, v122
	v_add_f32_e32 v116, v116, v117
	v_mul_f32_e32 v117, v119, v119
	v_fmac_f32_e32 v117, v118, v118
	v_add_f32_e32 v116, v117, v116
	v_mul_f32_e32 v117, v129, v129
	v_fmac_f32_e32 v117, v128, v128
	v_add_f32_e32 v116, v117, v116
	v_add_f32_e32 v126, v179, v116
	v_cvt_pk_bf16_f32 v116, v120, v121
	v_cvt_pk_bf16_f32 v117, v122, v123
	v_cvt_pk_bf16_f32 v118, v118, v119
	v_cvt_pk_bf16_f32 v119, v128, v129
	global_store_dwordx4 v[124:125], v[116:119], off offset:256
	ds_bpermute_b32 v116, v208, v126
	s_waitcnt lgkmcnt(0)
	v_add_f32_e32 v116, v126, v116
	ds_bpermute_b32 v117, v207, v116
	s_and_saveexec_b64 s[74:75], s[38:39]
	s_cbranch_execz .LBB0_649
	s_lshl_b64 s[30:31], s[72:73], 20
	s_waitcnt lgkmcnt(0)
	v_add_f32_e32 v118, v116, v117
	s_add_u32 s30, s40, s30
	v_lshlrev_b32_e32 v116, 6, v178
	s_addc_u32 s31, s41, s31
	v_and_b32_e32 v116, 0x33c0, v116
	v_mov_b32_e32 v117, v66
	v_lshl_add_u64 v[116:117], s[30:31], 0, v[116:117]
	v_lshl_add_u64 v[116:117], s[70:71], 2, v[116:117]
	s_lshl_b32 s84, s24, 2
	v_lshl_add_u64 v[116:117], v[116:117], 0, s[84:85]
	global_store_dword v[116:117], v118, off

; __device__ __forceinline__ unsigned cvt_pk_bf16(float lo, float hi) { f32x2c v = {lo, hi}; bf16x2c b = __builtin_convertvector(v, bf16x2c); return __builtin_bit_cast(unsigned, b); }
; __device__ __forceinline__ float bf_lo(unsigned w) { return __uint_as_float(w << 16); }
; __device__ __forceinline__ float bf_hi(unsigned w) { return __uint_as_float(w & 0xffff0000u); }
;     __device__ __forceinline__ void operator()(f32x4 (&acc)[2][2][4][2], const Unit& u, int wr, int wc, int fr, int fq) const {
;     ...
;         for (int ai = 0; ai < 2; ++ai) {
;             u32x4 bb[4][2];
; #pragma unroll
;             for (int m = 0; m < 4; ++m)
; #pragma unroll
;                 for (int bj = 0; bj < 2; ++bj) bb[m][bj] = *(const u32x4*)(baseh + (size_t)(row0 + ai * HALF + m * 16) * 1024 + col0 + bj * HALF);
; #pragma unroll
;             for (int m = 0; m < 4; ++m) {
;                 const int row = row0 + ai * HALF + m * 16; float s = 0.f;
; #pragma unroll
;                 for (int bj = 0; bj < 2; ++bj) {
;                     const u32x4 b = bb[m][bj];
;                     const f32x4 v0 = acc[ai][bj][m][0] + (f32x4){bf_lo(b.x), bf_hi(b.x), bf_lo(b.y), bf_hi(b.y)}, v1 = acc[ai][bj][m][1] + (f32x4){bf_lo(b.z), bf_hi(b.z), bf_lo(b.w), bf_hi(b.w)};
;                     s += (v0[0] * v0[0] + v0[1] * v0[1]) + (v0[2] * v0[2] + v0[3] * v0[3]) + (v1[0] * v1[0] + v1[1] * v1[1]) + (v1[2] * v1[2] + v1[3] * v1[3]);
;                     u32x4 w; w.x = cvt_pk_bf16(v0[0], v0[1]); w.y = cvt_pk_bf16(v0[2], v0[3]); w.z = cvt_pk_bf16(v1[0], v1[1]); w.w = cvt_pk_bf16(v1[2], v1[3]);
;                     *(u32x4*)(outh + (size_t)row * 1024 + col0 + bj * HALF) = w;
;                 }
;                 s += __shfl_xor(s, 16); s += __shfl_xor(s, 32);
;                 if (fq == 0) ssq[(size_t)(row >> 8) * pstride + (row & 255) * 16 + u.pn * 4 + wc] = s;
.LBB0_655:
	s_or_b64 exec, exec, s[74:75]
	v_add_u32_e32 v108, 0x80, v178
	v_ashrrev_i32_e32 v109, 31, v108
	v_lshlrev_b64 v[112:113], 11, v[108:109]
	s_waitcnt lgkmcnt(0)
	v_lshl_add_u64 v[68:69], v[180:181], 0, v[112:113]
	s_waitcnt vmcnt(8)
	v_mov_b32_e32 v114, v220
	v_mov_b32_e32 v115, v221
	v_mov_b32_e32 v116, v222
	v_mov_b32_e32 v117, v223
	v_mov_b32_e32 v92, v224
	v_mov_b32_e32 v93, v225
	v_mov_b32_e32 v94, v226
	v_mov_b32_e32 v95, v227
	v_add_u32_e32 v104, 0x90, v178
	v_ashrrev_i32_e32 v105, 31, v104
	v_add_u32_e32 v100, 0xa0, v178
	v_lshlrev_b64 v[106:107], 11, v[104:105]
	v_ashrrev_i32_e32 v101, 31, v100
	v_add_u32_e32 v96, 0xb0, v178
	v_lshl_add_u64 v[68:69], v[180:181], 0, v[106:107]
	v_lshlrev_b64 v[102:103], 11, v[100:101]
	v_ashrrev_i32_e32 v97, 31, v96
	v_mov_b32_e32 v88, v228
	v_mov_b32_e32 v89, v229
	v_mov_b32_e32 v90, v230
	v_mov_b32_e32 v91, v231
	v_mov_b32_e32 v84, v232
	v_mov_b32_e32 v85, v233
	v_mov_b32_e32 v86, v234
	v_mov_b32_e32 v87, v235
	v_lshl_add_u64 v[68:69], v[180:181], 0, v[102:103]
	v_lshlrev_b64 v[98:99], 11, v[96:97]
	v_mov_b32_e32 v80, v244
	v_mov_b32_e32 v81, v245
	v_mov_b32_e32 v82, v246
	v_mov_b32_e32 v83, v247
	v_mov_b32_e32 v76, v248
	v_mov_b32_e32 v77, v249
	v_mov_b32_e32 v78, v250
	v_mov_b32_e32 v79, v251
	v_lshl_add_u64 v[68:69], v[180:181], 0, v[98:99]
	v_mov_b32_e32 v72, v252
	v_mov_b32_e32 v73, v253
	v_mov_b32_e32 v74, v254
	v_mov_b32_e32 v75, v255
	s_nop 0
	v_mov_b32_e32 v68, v172
	v_mov_b32_e32 v69, v173
	v_mov_b32_e32 v70, v174
	v_mov_b32_e32 v71, v175
	ds_read_b128 v[172:175], v209
	s_waitcnt lgkmcnt(0)
	v_ashrrev_i32_e32 v110, 8, v108
	v_ashrrev_i32_e32 v111, 31, v110
	v_lshlrev_b32_e32 v118, 16, v114
	v_and_b32_e32 v119, 0xffff0000, v114
	v_lshlrev_b32_e32 v114, 16, v115
	v_and_b32_e32 v115, 0xffff0000, v115
	v_pk_add_f32 v[64:65], v[64:65], v[114:115]
	v_pk_add_f32 v[62:63], v[62:63], v[118:119]
	v_lshlrev_b32_e32 v114, 16, v116
	v_and_b32_e32 v115, 0xffff0000, v116
	v_lshlrev_b32_e32 v116, 16, v117
	v_and_b32_e32 v117, 0xffff0000, v117
	v_pk_add_f32 v[116:117], v[60:61], v[116:117]
	v_pk_add_f32 v[60:61], v[58:59], v[114:115]
	v_mul_f32_e32 v58, v63, v63
	v_mul_f32_e32 v59, v65, v65
	v_fmac_f32_e32 v58, v62, v62
	v_fmac_f32_e32 v59, v64, v64
	v_add_f32_e32 v58, v58, v59
	v_mul_f32_e32 v59, v61, v61
	v_fmac_f32_e32 v59, v60, v60
	v_add_f32_e32 v58, v59, v58
	v_mul_f32_e32 v59, v117, v117
	v_fmac_f32_e32 v59, v116, v116
	v_add_f32_e32 v97, v59, v58
	v_cvt_pk_bf16_f32 v58, v62, v63
	v_lshl_add_u64 v[62:63], s[90:91], 0, v[112:113]
	v_cvt_pk_bf16_f32 v59, v64, v65
	v_cvt_pk_bf16_f32 v60, v60, v61
	v_cvt_pk_bf16_f32 v61, v116, v117
	v_lshl_add_u64 v[62:63], v[176:177], 1, v[62:63]
	global_store_dwordx4 v[62:63], v[58:61], off
	s_nop 0
	v_lshlrev_b32_e32 v58, 16, v92
	v_and_b32_e32 v59, 0xffff0000, v92
	v_lshlrev_b32_e32 v60, 16, v93
	v_and_b32_e32 v61, 0xffff0000, v93
	v_pk_add_f32 v[56:57], v[56:57], v[60:61]
	v_pk_add_f32 v[54:55], v[54:55], v[58:59]
	v_lshlrev_b32_e32 v58, 16, v94
	v_and_b32_e32 v59, 0xffff0000, v94
	v_lshlrev_b32_e32 v60, 16, v95
	v_and_b32_e32 v61, 0xffff0000, v95
	v_pk_add_f32 v[60:61], v[52:53], v[60:61]
	v_pk_add_f32 v[52:53], v[50:51], v[58:59]
	v_mul_f32_e32 v50, v55, v55
	v_mul_f32_e32 v51, v57, v57
	v_fmac_f32_e32 v50, v54, v54
	v_fmac_f32_e32 v51, v56, v56
	v_add_f32_e32 v50, v50, v51
	v_mul_f32_e32 v51, v53, v53
	v_fmac_f32_e32 v51, v52, v52
	v_add_f32_e32 v50, v51, v50
	v_mul_f32_e32 v51, v61, v61
	v_fmac_f32_e32 v51, v60, v60
	v_add_f32_e32 v50, v51, v50
	v_add_f32_e32 v58, v97, v50
	v_cvt_pk_bf16_f32 v50, v54, v55
	v_cvt_pk_bf16_f32 v51, v56, v57
	v_cvt_pk_bf16_f32 v52, v52, v53
	v_cvt_pk_bf16_f32 v53, v60, v61
	global_store_dwordx4 v[62:63], v[50:53], off offset:256
	ds_bpermute_b32 v50, v208, v58
	s_waitcnt lgkmcnt(0)
	v_add_f32_e32 v52, v58, v50
	ds_bpermute_b32 v53, v207, v52
	v_lshlrev_b64 v[50:51], 20, v[110:111]
	v_lshl_add_u64 v[50:51], s[40:41], 0, v[50:51]
	s_and_saveexec_b64 s[72:73], s[38:39]
	s_cbranch_execz .LBB0_657
	s_waitcnt lgkmcnt(0)
	v_add_f32_e32 v54, v52, v53
	v_lshlrev_b32_e32 v52, 6, v108
	v_and_b32_e32 v52, 0x33c0, v52
	v_mov_b32_e32 v53, v66
	v_lshl_add_u64 v[52:53], v[50:51], 0, v[52:53]
	v_lshl_add_u64 v[52:53], s[70:71], 2, v[52:53]
	s_lshl_b32 s84, s24, 2
	v_lshl_add_u64 v[52:53], v[52:53], 0, s[84:85]
	global_store_dword v[52:53], v54, off
; __device__ __forceinline__ unsigned cvt_pk_bf16(float lo, float hi) { f32x2c v = {lo, hi}; bf16x2c b = __builtin_convertvector(v, bf16x2c); return __builtin_bit_cast(unsigned, b); }
; __device__ __forceinline__ float bf_lo(unsigned w) { return __uint_as_float(w << 16); }
; __device__ __forceinline__ float bf_hi(unsigned w) { return __uint_as_float(w & 0xffff0000u); }
;     __device__ __forceinline__ void operator()(f32x4 (&acc)[2][2][4][2], const Unit& u, int wr, int wc, int fr, int fq) const {
;     ...
;             for (int m = 0; m < 4; ++m) {
;                 const int row = row0 + ai * HALF + m * 16; float s = 0.f;
; #pragma unroll
;                 for (int bj = 0; bj < 2; ++bj) {
;                     const u32x4 b = bb[m][bj];
;                     const f32x4 v0 = acc[ai][bj][m][0] + (f32x4){bf_lo(b.x), bf_hi(b.x), bf_lo(b.y), bf_hi(b.y)}, v1 = acc[ai][bj][m][1] + (f32x4){bf_lo(b.z), bf_hi(b.z), bf_lo(b.w), bf_hi(b.w)};
;                     s += (v0[0] * v0[0] + v0[1] * v0[1]) + (v0[2] * v0[2] + v0[3] * v0[3]) + (v1[0] * v1[0] + v1[1] * v1[1]) + (v1[2] * v1[2] + v1[3] * v1[3]);
;                     u32x4 w; w.x = cvt_pk_bf16(v0[0], v0[1]); w.y = cvt_pk_bf16(v0[2], v0[3]); w.z = cvt_pk_bf16(v1[0], v1[1]); w.w = cvt_pk_bf16(v1[2], v1[3]);
;                     *(u32x4*)(outh + (size_t)row * 1024 + col0 + bj * HALF) = w;
;                 }
;                 s += __shfl_xor(s, 16); s += __shfl_xor(s, 32);
;                 if (fq == 0) ssq[(size_t)(row >> 8) * pstride + (row & 255) * 16 + u.pn * 4 + wc] = s;
.LBB0_657:
	s_or_b64 exec, exec, s[72:73]
	v_lshlrev_b32_e32 v52, 16, v88
	s_waitcnt lgkmcnt(0)
	v_and_b32_e32 v53, 0xffff0000, v88
	v_lshlrev_b32_e32 v54, 16, v89
	v_and_b32_e32 v55, 0xffff0000, v89
	v_pk_add_f32 v[48:49], v[48:49], v[54:55]
	v_pk_add_f32 v[46:47], v[46:47], v[52:53]
	v_lshlrev_b32_e32 v52, 16, v90
	v_and_b32_e32 v53, 0xffff0000, v90
	v_lshlrev_b32_e32 v54, 16, v91
	v_and_b32_e32 v55, 0xffff0000, v91
	v_pk_add_f32 v[54:55], v[44:45], v[54:55]
	v_pk_add_f32 v[44:45], v[42:43], v[52:53]
	v_mul_f32_e32 v42, v47, v47
	v_mul_f32_e32 v43, v49, v49
	v_fmac_f32_e32 v42, v46, v46
	v_fmac_f32_e32 v43, v48, v48
	v_add_f32_e32 v42, v42, v43
	v_mul_f32_e32 v43, v45, v45
	v_fmac_f32_e32 v43, v44, v44
	v_add_f32_e32 v42, v43, v42
	v_mul_f32_e32 v43, v55, v55
	v_fmac_f32_e32 v43, v54, v54
	v_add_f32_e32 v52, v43, v42
	v_cvt_pk_bf16_f32 v42, v46, v47
	v_cvt_pk_bf16_f32 v43, v48, v49
	v_lshlrev_b32_e32 v46, 16, v84
	v_and_b32_e32 v47, 0xffff0000, v84
	v_lshlrev_b32_e32 v48, 16, v85
	v_and_b32_e32 v49, 0xffff0000, v85
	v_pk_add_f32 v[40:41], v[40:41], v[48:49]
	v_pk_add_f32 v[38:39], v[38:39], v[46:47]
	v_lshlrev_b32_e32 v46, 16, v86
	v_and_b32_e32 v47, 0xffff0000, v86
	v_pk_add_f32 v[46:47], v[34:35], v[46:47]
	v_mul_f32_e32 v34, v39, v39
	v_mul_f32_e32 v35, v41, v41
	v_fmac_f32_e32 v34, v38, v38
	v_fmac_f32_e32 v35, v40, v40
	v_lshlrev_b32_e32 v48, 16, v87
	v_and_b32_e32 v49, 0xffff0000, v87
	v_add_f32_e32 v34, v34, v35
	v_mul_f32_e32 v35, v47, v47
	v_pk_add_f32 v[48:49], v[36:37], v[48:49]
	v_fmac_f32_e32 v35, v46, v46
	v_add_f32_e32 v34, v35, v34
	v_mul_f32_e32 v35, v49, v49
	v_fmac_f32_e32 v35, v48, v48
	v_add_f32_e32 v34, v35, v34
	v_add_f32_e32 v37, v52, v34
	v_cvt_pk_bf16_f32 v44, v44, v45
	v_cvt_pk_bf16_f32 v45, v54, v55
	ds_bpermute_b32 v54, v208, v37
	v_lshl_add_u64 v[34:35], s[90:91], 0, v[106:107]
	v_lshl_add_u64 v[52:53], v[176:177], 1, v[34:35]
	v_cvt_pk_bf16_f32 v36, v38, v39
	v_cvt_pk_bf16_f32 v38, v46, v47
	s_waitcnt lgkmcnt(0)
	v_add_f32_e32 v34, v37, v54
	ds_bpermute_b32 v35, v207, v34
	v_cvt_pk_bf16_f32 v37, v40, v41
	v_cvt_pk_bf16_f32 v39, v48, v49
	global_store_dwordx4 v[52:53], v[42:45], off
	global_store_dwordx4 v[52:53], v[36:39], off offset:256
	s_and_saveexec_b64 s[72:73], s[38:39]
	s_cbranch_execz .LBB0_659
	s_waitcnt lgkmcnt(0)
	v_add_f32_e32 v36, v34, v35
	v_lshlrev_b32_e32 v34, 6, v104
	v_and_b32_e32 v34, 0x37c0, v34
	v_mov_b32_e32 v35, v66
	v_lshl_add_u64 v[34:35], v[50:51], 0, v[34:35]
	v_lshl_add_u64 v[34:35], s[70:71], 2, v[34:35]
	s_lshl_b32 s84, s24, 2
	v_lshl_add_u64 v[34:35], v[34:35], 0, s[84:85]
	global_store_dword v[34:35], v36, off
; __device__ __forceinline__ unsigned cvt_pk_bf16(float lo, float hi) { f32x2c v = {lo, hi}; bf16x2c b = __builtin_convertvector(v, bf16x2c); return __builtin_bit_cast(unsigned, b); }
; __device__ __forceinline__ float bf_lo(unsigned w) { return __uint_as_float(w << 16); }
; __device__ __forceinline__ float bf_hi(unsigned w) { return __uint_as_float(w & 0xffff0000u); }
;     __device__ __forceinline__ void operator()(f32x4 (&acc)[2][2][4][2], const Unit& u, int wr, int wc, int fr, int fq) const {
;     ...
;             for (int m = 0; m < 4; ++m) {
;                 const int row = row0 + ai * HALF + m * 16; float s = 0.f;
; #pragma unroll
;                 for (int bj = 0; bj < 2; ++bj) {
;                     const u32x4 b = bb[m][bj];
;                     const f32x4 v0 = acc[ai][bj][m][0] + (f32x4){bf_lo(b.x), bf_hi(b.x), bf_lo(b.y), bf_hi(b.y)}, v1 = acc[ai][bj][m][1] + (f32x4){bf_lo(b.z), bf_hi(b.z), bf_lo(b.w), bf_hi(b.w)};
;                     s += (v0[0] * v0[0] + v0[1] * v0[1]) + (v0[2] * v0[2] + v0[3] * v0[3]) + (v1[0] * v1[0] + v1[1] * v1[1]) + (v1[2] * v1[2] + v1[3] * v1[3]);
;                     u32x4 w; w.x = cvt_pk_bf16(v0[0], v0[1]); w.y = cvt_pk_bf16(v0[2], v0[3]); w.z = cvt_pk_bf16(v1[0], v1[1]); w.w = cvt_pk_bf16(v1[2], v1[3]);
;                     *(u32x4*)(outh + (size_t)row * 1024 + col0 + bj * HALF) = w;
;                 }
;                 s += __shfl_xor(s, 16); s += __shfl_xor(s, 32);
;                 if (fq == 0) ssq[(size_t)(row >> 8) * pstride + (row & 255) * 16 + u.pn * 4 + wc] = s;
.LBB0_659:
	s_or_b64 exec, exec, s[72:73]
	v_lshlrev_b32_e32 v34, 16, v80
	s_waitcnt lgkmcnt(0)
	v_and_b32_e32 v35, 0xffff0000, v80
	v_lshlrev_b32_e32 v36, 16, v81
	v_and_b32_e32 v37, 0xffff0000, v81
	v_pk_add_f32 v[32:33], v[32:33], v[36:37]
	v_pk_add_f32 v[30:31], v[30:31], v[34:35]
	v_lshlrev_b32_e32 v34, 16, v82
	v_and_b32_e32 v35, 0xffff0000, v82
	v_lshlrev_b32_e32 v36, 16, v83
	v_and_b32_e32 v37, 0xffff0000, v83
	v_pk_add_f32 v[36:37], v[28:29], v[36:37]
	v_pk_add_f32 v[28:29], v[26:27], v[34:35]
	v_mul_f32_e32 v26, v31, v31
	v_mul_f32_e32 v27, v33, v33
	v_fmac_f32_e32 v26, v30, v30
	v_fmac_f32_e32 v27, v32, v32
	v_add_f32_e32 v26, v26, v27
	v_mul_f32_e32 v27, v29, v29
	v_fmac_f32_e32 v27, v28, v28
	v_add_f32_e32 v26, v27, v26
	v_mul_f32_e32 v27, v37, v37
	v_fmac_f32_e32 v27, v36, v36
	v_add_f32_e32 v34, v27, v26
	v_cvt_pk_bf16_f32 v26, v30, v31
	v_cvt_pk_bf16_f32 v27, v32, v33
	v_lshlrev_b32_e32 v30, 16, v76
	v_and_b32_e32 v31, 0xffff0000, v76
	v_lshlrev_b32_e32 v32, 16, v77
	v_and_b32_e32 v33, 0xffff0000, v77
	v_pk_add_f32 v[24:25], v[24:25], v[32:33]
	v_pk_add_f32 v[22:23], v[22:23], v[30:31]
	v_lshlrev_b32_e32 v30, 16, v78
	v_and_b32_e32 v31, 0xffff0000, v78
	v_pk_add_f32 v[30:31], v[18:19], v[30:31]
	v_mul_f32_e32 v18, v23, v23
	v_mul_f32_e32 v19, v25, v25
	v_fmac_f32_e32 v18, v22, v22
	v_fmac_f32_e32 v19, v24, v24
	v_lshlrev_b32_e32 v32, 16, v79
	v_and_b32_e32 v33, 0xffff0000, v79
	v_add_f32_e32 v18, v18, v19
	v_mul_f32_e32 v19, v31, v31
	v_pk_add_f32 v[32:33], v[20:21], v[32:33]
	v_fmac_f32_e32 v19, v30, v30
	v_add_f32_e32 v18, v19, v18
	v_mul_f32_e32 v19, v33, v33
	v_fmac_f32_e32 v19, v32, v32
	v_add_f32_e32 v18, v19, v18
	v_add_f32_e32 v21, v34, v18
	v_cvt_pk_bf16_f32 v28, v28, v29
	v_cvt_pk_bf16_f32 v29, v36, v37
	ds_bpermute_b32 v36, v208, v21
	v_lshl_add_u64 v[18:19], s[90:91], 0, v[102:103]
	v_lshl_add_u64 v[34:35], v[176:177], 1, v[18:19]
	v_cvt_pk_bf16_f32 v20, v22, v23
	v_cvt_pk_bf16_f32 v22, v30, v31
	s_waitcnt lgkmcnt(0)
	v_add_f32_e32 v18, v21, v36
	ds_bpermute_b32 v19, v207, v18
	v_cvt_pk_bf16_f32 v21, v24, v25
	v_cvt_pk_bf16_f32 v23, v32, v33
	global_store_dwordx4 v[34:35], v[26:29], off
	global_store_dwordx4 v[34:35], v[20:23], off offset:256
	s_and_saveexec_b64 s[72:73], s[38:39]
	s_cbranch_execz .LBB0_661
	s_waitcnt lgkmcnt(0)
	v_add_f32_e32 v20, v18, v19
	v_lshlrev_b32_e32 v18, 6, v100
	v_and_b32_e32 v18, 0x3bc0, v18
	v_mov_b32_e32 v19, v66
	v_lshl_add_u64 v[18:19], v[50:51], 0, v[18:19]
	v_lshl_add_u64 v[18:19], s[70:71], 2, v[18:19]
	s_lshl_b32 s84, s24, 2
	v_lshl_add_u64 v[18:19], v[18:19], 0, s[84:85]
	global_store_dword v[18:19], v20, off
.LBB0_661:
	s_or_b64 exec, exec, s[72:73]
	v_lshlrev_b32_e32 v18, 16, v72
	s_waitcnt lgkmcnt(0)
	v_and_b32_e32 v19, 0xffff0000, v72
	v_lshlrev_b32_e32 v20, 16, v73
	v_and_b32_e32 v21, 0xffff0000, v73
	v_pk_add_f32 v[16:17], v[16:17], v[20:21]
	v_pk_add_f32 v[14:15], v[14:15], v[18:19]
	v_lshlrev_b32_e32 v18, 16, v74
	v_and_b32_e32 v19, 0xffff0000, v74
	v_lshlrev_b32_e32 v20, 16, v75
	v_and_b32_e32 v21, 0xffff0000, v75
	v_pk_add_f32 v[20:21], v[12:13], v[20:21]
	v_pk_add_f32 v[12:13], v[10:11], v[18:19]
	v_mul_f32_e32 v10, v15, v15
	v_mul_f32_e32 v11, v17, v17
	v_fmac_f32_e32 v10, v14, v14
	v_fmac_f32_e32 v11, v16, v16
	v_add_f32_e32 v10, v10, v11
	v_mul_f32_e32 v11, v13, v13
	v_fmac_f32_e32 v11, v12, v12
	v_add_f32_e32 v10, v11, v10
	v_mul_f32_e32 v11, v21, v21
	v_fmac_f32_e32 v11, v20, v20
	v_add_f32_e32 v18, v11, v10
	v_cvt_pk_bf16_f32 v10, v14, v15
	v_cvt_pk_bf16_f32 v11, v16, v17
	v_lshlrev_b32_e32 v14, 16, v68
	v_and_b32_e32 v15, 0xffff0000, v68
	v_lshlrev_b32_e32 v16, 16, v69
	v_and_b32_e32 v17, 0xffff0000, v69
	v_pk_add_f32 v[8:9], v[8:9], v[16:17]
	v_pk_add_f32 v[6:7], v[6:7], v[14:15]
	v_lshlrev_b32_e32 v14, 16, v70
	v_and_b32_e32 v15, 0xffff0000, v70
	v_pk_add_f32 v[14:15], v[2:3], v[14:15]
	v_mul_f32_e32 v2, v7, v7
	v_mul_f32_e32 v3, v9, v9
	v_fmac_f32_e32 v2, v6, v6
	v_fmac_f32_e32 v3, v8, v8
	v_lshlrev_b32_e32 v16, 16, v71
	v_and_b32_e32 v17, 0xffff0000, v71
	v_add_f32_e32 v2, v2, v3
	v_mul_f32_e32 v3, v15, v15
	v_pk_add_f32 v[16:17], v[4:5], v[16:17]
	v_fmac_f32_e32 v3, v14, v14
	v_add_f32_e32 v2, v3, v2
	v_mul_f32_e32 v3, v17, v17
	v_fmac_f32_e32 v3, v16, v16
	v_add_f32_e32 v2, v3, v2
	v_add_f32_e32 v5, v18, v2
	v_cvt_pk_bf16_f32 v12, v12, v13
	v_cvt_pk_bf16_f32 v13, v20, v21
	ds_bpermute_b32 v20, v208, v5
	v_lshl_add_u64 v[2:3], s[90:91], 0, v[98:99]
	v_lshl_add_u64 v[18:19], v[176:177], 1, v[2:3]
	v_cvt_pk_bf16_f32 v4, v6, v7
	v_cvt_pk_bf16_f32 v6, v14, v15
	s_waitcnt lgkmcnt(0)
	v_add_f32_e32 v2, v5, v20
	ds_bpermute_b32 v3, v207, v2
	v_cvt_pk_bf16_f32 v5, v8, v9
	v_cvt_pk_bf16_f32 v7, v16, v17
	global_store_dwordx4 v[18:19], v[10:13], off
	global_store_dwordx4 v[18:19], v[4:7], off offset:256
	s_and_saveexec_b64 s[72:73], s[38:39]
	s_cbranch_execz .LBB0_638
	s_waitcnt lgkmcnt(0)
	v_add_f32_e32 v4, v2, v3
	v_lshlrev_b32_e32 v2, 6, v96
	v_and_b32_e32 v2, 0x3fc0, v2
	v_mov_b32_e32 v3, v66
	v_lshl_add_u64 v[2:3], v[50:51], 0, v[2:3]
	v_lshl_add_u64 v[2:3], s[70:71], 2, v[2:3]
	s_lshl_b32 s84, s24, 2
	v_lshl_add_u64 v[2:3], v[2:3], 0, s[84:85]
	global_store_dword v[2:3], v4, off
	s_branch .LBB0_638

; #define PG8_STAGE(bufoff, gbase, voff) do { _Pragma("unroll") for (int _i = 0; _i < 2; ++_i) \
;         __builtin_amdgcn_global_load_lds((const unsigned*)((const char*)(gbase) + (voff)[_i]), (PG8_LAS unsigned*)(lds + (bufoff) + ldsw + _i * 8192), 16, 0, 0); } while (0)
; #define PG8_LDA(dst, b, h) do { _Pragma("unroll") for (int m = 0; m < 4; ++m) _Pragma("unroll") for (int k = 0; k < 2; ++k) dst[m][k] = *(const PG8_LAS bf16x8*)(lds + PG8_SA(b, h) + aoff + m * 2048 + k * 1024); } while (0)
; #define PG8_LDB(dst, b, h) do { _Pragma("unroll") for (int n = 0; n < 2; ++n) _Pragma("unroll") for (int k = 0; k < 2; ++k) dst[n][k] = *(const PG8_LAS bf16x8*)(lds + PG8_SB(b, h) + boff + n * 2048 + k * 1024); } while (0)
; #define PG8_MMA(ai, bj, At, Bt) do { __builtin_amdgcn_s_setprio(1); _Pragma("unroll") for (int m = 0; m < 4; ++m) _Pragma("unroll") for (int n = 0; n < 2; ++n) _Pragma("unroll") for (int k = 0; k < 2; ++k) \
;         acc[ai][bj][m][n] = __builtin_amdgcn_mfma_f32_16x16x32_bf16(Bt[n][k], At[m][k], acc[ai][bj][m][n], 0, 0, 0); __builtin_amdgcn_s_setprio(0); } while (0)
; #define PG8_WAIT_V(n) asm volatile("s_waitcnt vmcnt(" #n ")" ::: "memory")
; #define PG8_WAIT_L(n) asm volatile("s_waitcnt lgkmcnt(" #n ")" ::: "memory")
; #define PG8_BAR __builtin_amdgcn_s_barrier()
; #define PG8_SCHED __builtin_amdgcn_sched_barrier(0)
; template <class Epi, class Sched, bool ALIGN_EPI = false, bool SP2 = false>
; __device__ __forceinline__ void gemm_phase(PG8_LAS unsigned char* lds, const Gemm g, const Sched& S, const Epi& E) {
;     ...
;             PG8_LDB(B0, 0, 0); PG8_LDB(B1, 0, 1); PG8_SCHED; PG8_LDA(At, 0, 0); PG8_STAGE(PG8_SA(1, 1), a1 + hstep, voffA);
;             PG8_WAIT_V(8); PG8_WAIT_L(0); PG8_BAR; PG8_MMA(0, 0, At, B0); PG8_MMA(0, 1, At, B1); PG8_BAR; PG8_SCHED;
;             PG8_LDA(At, 0, 1); PG8_STAGE(PG8_SB(0, 0), b2, voffB); PG8_STAGE(PG8_SB(0, 1), b2 + hstepB, voffB); PG8_STAGE(PG8_SA(0, 0), a2, voffA);
;             PG8_WAIT_V(8); PG8_WAIT_L(0); PG8_BAR; PG8_MMA(1, 0, At, B0); PG8_MMA(1, 1, At, B1); PG8_BAR; PG8_SCHED;
.LBB0_912:
	s_add_u32 s50, s48, 0x100
	s_addc_u32 s51, s49, 0
	s_add_i32 s35, 0, 0x10000
	s_cmp_eq_u32 s34, 40
	s_cselect_b32 s59, s47, s51
	s_cselect_b32 s58, s46, s50
	s_cselect_b32 s57, s39, s31
	s_cselect_b32 s56, s38, s30
	s_add_i32 s73, 0, 0x14000
	v_add_u32_e32 v144, s35, v204
	v_add_u32_e32 v176, s73, v204
	ds_read_b128 v[132:135], v144
	ds_read_b128 v[136:139], v144 offset:1024
	ds_read_b128 v[140:143], v144 offset:2048
	ds_read_b128 v[144:147], v144 offset:3072
	ds_read_b128 v[148:151], v176
	ds_read_b128 v[152:155], v176 offset:1024
	ds_read_b128 v[156:159], v176 offset:2048
	ds_read_b128 v[176:179], v176 offset:3072
	v_lshl_add_u64 v[192:193], s[48:49], 0, v[172:173]
	s_add_i32 m0, s62, 0xc000
	ds_read_b128 v[180:183], v206
	ds_read_b128 v[184:187], v206 offset:1024
	ds_read_b128 v[188:191], v206 offset:2048
	ds_read_b128 v[208:211], v206 offset:3072
	ds_read_b128 v[212:215], v206 offset:4096
	ds_read_b128 v[216:219], v206 offset:5120
	ds_read_b128 v[220:223], v206 offset:6144
	ds_read_b128 v[224:227], v206 offset:7168
	global_load_lds_dwordx4 v[192:193], off
	v_lshl_add_u64 v[192:193], s[48:49], 0, v[174:175]
	s_add_i32 m0, s62, 0xe000
	s_nop 0
	global_load_lds_dwordx4 v[192:193], off
	s_waitcnt vmcnt(8)
	s_waitcnt lgkmcnt(0)
	s_barrier
	s_setprio 1
	s_waitcnt lgkmcnt(0)
	v_mfma_f32_16x16x32_bf16 v[128:131], v[132:135], v[180:183], v[128:131]
	v_mfma_f32_16x16x32_bf16 v[124:127], v[140:143], v[180:183], v[124:127]
	v_mfma_f32_16x16x32_bf16 v[112:115], v[132:135], v[188:191], v[112:115]
	v_mfma_f32_16x16x32_bf16 v[108:111], v[140:143], v[188:191], v[108:111]
	v_mfma_f32_16x16x32_bf16 v[96:99], v[132:135], v[212:215], v[96:99]
	v_mfma_f32_16x16x32_bf16 v[92:95], v[140:143], v[212:215], v[92:95]
	v_mfma_f32_16x16x32_bf16 v[80:83], v[132:135], v[220:223], v[80:83]
	v_mfma_f32_16x16x32_bf16 v[76:79], v[140:143], v[220:223], v[76:79]
	v_mfma_f32_16x16x32_bf16 v[128:131], v[136:139], v[184:187], v[128:131]
	v_mfma_f32_16x16x32_bf16 v[124:127], v[144:147], v[184:187], v[124:127]
	v_mfma_f32_16x16x32_bf16 v[112:115], v[136:139], v[208:211], v[112:115]
	v_mfma_f32_16x16x32_bf16 v[108:111], v[144:147], v[208:211], v[108:111]
	v_mfma_f32_16x16x32_bf16 v[96:99], v[136:139], v[216:219], v[96:99]
	v_mfma_f32_16x16x32_bf16 v[92:95], v[144:147], v[216:219], v[92:95]
	v_mfma_f32_16x16x32_bf16 v[80:83], v[136:139], v[224:227], v[80:83]
	v_mfma_f32_16x16x32_bf16 v[76:79], v[144:147], v[224:227], v[76:79]
	s_setprio 0
	s_setprio 1
	v_mfma_f32_16x16x32_bf16 v[120:123], v[148:151], v[180:183], v[120:123]
	v_mfma_f32_16x16x32_bf16 v[116:119], v[156:159], v[180:183], v[116:119]
	v_mfma_f32_16x16x32_bf16 v[104:107], v[148:151], v[188:191], v[104:107]
	v_mfma_f32_16x16x32_bf16 v[100:103], v[156:159], v[188:191], v[100:103]
	v_mfma_f32_16x16x32_bf16 v[88:91], v[148:151], v[212:215], v[88:91]
	v_mfma_f32_16x16x32_bf16 v[84:87], v[156:159], v[212:215], v[84:87]
	v_mfma_f32_16x16x32_bf16 v[72:75], v[148:151], v[220:223], v[72:75]
	v_mfma_f32_16x16x32_bf16 v[68:71], v[156:159], v[220:223], v[68:71]
	v_mfma_f32_16x16x32_bf16 v[120:123], v[152:155], v[184:187], v[120:123]
	v_mfma_f32_16x16x32_bf16 v[116:119], v[176:179], v[184:187], v[116:119]
	v_mfma_f32_16x16x32_bf16 v[104:107], v[152:155], v[208:211], v[104:107]
	v_mfma_f32_16x16x32_bf16 v[100:103], v[176:179], v[208:211], v[100:103]
	v_mfma_f32_16x16x32_bf16 v[88:91], v[152:155], v[216:219], v[88:91]
	v_mfma_f32_16x16x32_bf16 v[84:87], v[176:179], v[216:219], v[84:87]
	v_mfma_f32_16x16x32_bf16 v[72:75], v[152:155], v[224:227], v[72:75]
	v_mfma_f32_16x16x32_bf16 v[68:71], v[176:179], v[224:227], v[68:71]
	s_setprio 0
	s_barrier
	s_add_i32 s35, s35, s61
	v_lshl_add_u64 v[192:193], s[56:57], 0, v[168:169]
	s_mov_b32 m0, s35
	ds_read_b128 v[180:183], v206 offset:16384
	ds_read_b128 v[184:187], v206 offset:17408
	ds_read_b128 v[188:191], v206 offset:18432
	ds_read_b128 v[208:211], v206 offset:19456
	ds_read_b128 v[212:215], v206 offset:20480
	ds_read_b128 v[216:219], v206 offset:21504
	ds_read_b128 v[220:223], v206 offset:22528
	ds_read_b128 v[224:227], v206 offset:23552
	global_load_lds_dwordx4 v[192:193], off
	s_add_i32 m0, s35, 0x2000
	s_add_u32 s48, s56, 0xb0000
	v_lshl_add_u64 v[228:229], s[56:57], 0, v[164:165]
	s_addc_u32 s49, s57, 0
	s_add_i32 s35, s73, s61
	global_load_lds_dwordx4 v[228:229], off
	v_lshl_add_u64 v[230:231], s[48:49], 0, v[168:169]
	s_mov_b32 m0, s35
	v_lshl_add_u64 v[232:233], s[58:59], 0, v[166:167]
	global_load_lds_dwordx4 v[230:231], off
	v_lshl_add_u64 v[230:231], s[48:49], 0, v[164:165]
	s_add_i32 m0, s35, 0x2000
	s_nop 0
	global_load_lds_dwordx4 v[230:231], off
	v_lshl_add_u64 v[230:231], s[58:59], 0, v[170:171]
	s_mov_b32 m0, s62
	s_nop 0
	global_load_lds_dwordx4 v[230:231], off
	s_mov_b32 m0, s63
	s_nop 0
	global_load_lds_dwordx4 v[232:233], off
	s_waitcnt vmcnt(8)
	s_waitcnt lgkmcnt(0)
	s_barrier
; #define PG8_STAGE(bufoff, gbase, voff) do { _Pragma("unroll") for (int _i = 0; _i < 2; ++_i) \
;         __builtin_amdgcn_global_load_lds((const unsigned*)((const char*)(gbase) + (voff)[_i]), (PG8_LAS unsigned*)(lds + (bufoff) + ldsw + _i * 8192), 16, 0, 0); } while (0)
; #define PG8_LDA(dst, b, h) do { _Pragma("unroll") for (int m = 0; m < 4; ++m) _Pragma("unroll") for (int k = 0; k < 2; ++k) dst[m][k] = *(const PG8_LAS bf16x8*)(lds + PG8_SA(b, h) + aoff + m * 2048 + k * 1024); } while (0)
; #define PG8_LDB(dst, b, h) do { _Pragma("unroll") for (int n = 0; n < 2; ++n) _Pragma("unroll") for (int k = 0; k < 2; ++k) dst[n][k] = *(const PG8_LAS bf16x8*)(lds + PG8_SB(b, h) + boff + n * 2048 + k * 1024); } while (0)
; #define PG8_MMA(ai, bj, At, Bt) do { __builtin_amdgcn_s_setprio(1); _Pragma("unroll") for (int m = 0; m < 4; ++m) _Pragma("unroll") for (int n = 0; n < 2; ++n) _Pragma("unroll") for (int k = 0; k < 2; ++k) \
;         acc[ai][bj][m][n] = __builtin_amdgcn_mfma_f32_16x16x32_bf16(Bt[n][k], At[m][k], acc[ai][bj][m][n], 0, 0, 0); __builtin_amdgcn_s_setprio(0); } while (0)
; #define PG8_WAIT_V(n) asm volatile("s_waitcnt vmcnt(" #n ")" ::: "memory")
; #define PG8_WAIT_L(n) asm volatile("s_waitcnt lgkmcnt(" #n ")" ::: "memory")
; #define PG8_BAR __builtin_amdgcn_s_barrier()
; #define PG8_SCHED __builtin_amdgcn_sched_barrier(0)
; template <class Epi, class Sched, bool ALIGN_EPI = false, bool SP2 = false>
; __device__ __forceinline__ void gemm_phase(PG8_LAS unsigned char* lds, const Gemm g, const Sched& S, const Epi& E) {
;     ...
;             PG8_WAIT_V(8); PG8_WAIT_L(0); PG8_BAR; PG8_MMA(1, 0, At, B0); PG8_MMA(1, 1, At, B1); PG8_BAR; PG8_SCHED;
;             PG8_LDB(B0, 1, 0); PG8_LDB(B1, 1, 1); PG8_SCHED; PG8_LDA(At, 1, 0); PG8_STAGE(PG8_SA(0, 1), a2 + hstep, voffA);
;             PG8_WAIT_V(8); PG8_WAIT_L(0); PG8_BAR; PG8_MMA(0, 0, At, B0); PG8_MMA(0, 1, At, B1); PG8_BAR; PG8_SCHED;
	s_setprio 1
	s_waitcnt lgkmcnt(0)
	v_mfma_f32_16x16x32_bf16 v[62:65], v[132:135], v[180:183], v[62:65]
	v_mfma_f32_16x16x32_bf16 v[58:61], v[140:143], v[180:183], v[58:61]
	v_mfma_f32_16x16x32_bf16 v[46:49], v[132:135], v[188:191], v[46:49]
	v_mfma_f32_16x16x32_bf16 v[42:45], v[140:143], v[188:191], v[42:45]
	v_mfma_f32_16x16x32_bf16 v[30:33], v[132:135], v[212:215], v[30:33]
	v_mfma_f32_16x16x32_bf16 v[26:29], v[140:143], v[212:215], v[26:29]
	v_mfma_f32_16x16x32_bf16 v[14:17], v[132:135], v[220:223], v[14:17]
	v_mfma_f32_16x16x32_bf16 v[10:13], v[140:143], v[220:223], v[10:13]
	v_mfma_f32_16x16x32_bf16 v[62:65], v[136:139], v[184:187], v[62:65]
	v_mfma_f32_16x16x32_bf16 v[58:61], v[144:147], v[184:187], v[58:61]
	v_mfma_f32_16x16x32_bf16 v[46:49], v[136:139], v[208:211], v[46:49]
	v_mfma_f32_16x16x32_bf16 v[42:45], v[144:147], v[208:211], v[42:45]
	v_mfma_f32_16x16x32_bf16 v[30:33], v[136:139], v[216:219], v[30:33]
	v_mfma_f32_16x16x32_bf16 v[26:29], v[144:147], v[216:219], v[26:29]
	v_mfma_f32_16x16x32_bf16 v[14:17], v[136:139], v[224:227], v[14:17]
	v_mfma_f32_16x16x32_bf16 v[10:13], v[144:147], v[224:227], v[10:13]
	s_setprio 0
	s_setprio 1
	v_mfma_f32_16x16x32_bf16 v[54:57], v[148:151], v[180:183], v[54:57]
	v_mfma_f32_16x16x32_bf16 v[50:53], v[156:159], v[180:183], v[50:53]
	v_mfma_f32_16x16x32_bf16 v[38:41], v[148:151], v[188:191], v[38:41]
	v_mfma_f32_16x16x32_bf16 v[34:37], v[156:159], v[188:191], v[34:37]
	v_mfma_f32_16x16x32_bf16 v[22:25], v[148:151], v[212:215], v[22:25]
	v_mfma_f32_16x16x32_bf16 v[18:21], v[156:159], v[212:215], v[18:21]
	v_mfma_f32_16x16x32_bf16 v[6:9], v[148:151], v[220:223], v[6:9]
	v_mfma_f32_16x16x32_bf16 v[2:5], v[156:159], v[220:223], v[2:5]
	v_mfma_f32_16x16x32_bf16 v[54:57], v[152:155], v[184:187], v[54:57]
	v_mfma_f32_16x16x32_bf16 v[50:53], v[176:179], v[184:187], v[50:53]
	v_mfma_f32_16x16x32_bf16 v[38:41], v[152:155], v[208:211], v[38:41]
	v_mfma_f32_16x16x32_bf16 v[34:37], v[176:179], v[208:211], v[34:37]
	v_mfma_f32_16x16x32_bf16 v[22:25], v[152:155], v[216:219], v[22:25]
	v_mfma_f32_16x16x32_bf16 v[18:21], v[176:179], v[216:219], v[18:21]
	v_mfma_f32_16x16x32_bf16 v[6:9], v[152:155], v[224:227], v[6:9]
	v_mfma_f32_16x16x32_bf16 v[2:5], v[176:179], v[224:227], v[2:5]
	s_setprio 0
	s_barrier
	s_add_i32 s35, 0, 0x18000
	s_add_i32 s73, 0, 0x1c000
	v_add_u32_e32 v144, s35, v204
	v_add_u32_e32 v176, s73, v204
	ds_read_b128 v[132:135], v144
	ds_read_b128 v[136:139], v144 offset:1024
	ds_read_b128 v[140:143], v144 offset:2048
	ds_read_b128 v[144:147], v144 offset:3072
	ds_read_b128 v[148:151], v176
	ds_read_b128 v[152:155], v176 offset:1024
	ds_read_b128 v[156:159], v176 offset:2048
	ds_read_b128 v[176:179], v176 offset:3072
	s_add_u32 s48, s58, 0xd0000
	s_addc_u32 s49, s59, 0
	s_mov_b32 m0, s66
	v_lshl_add_u64 v[234:235], s[48:49], 0, v[170:171]
	ds_read_b128 v[180:183], v206 offset:32768
	ds_read_b128 v[184:187], v206 offset:33792
	ds_read_b128 v[188:191], v206 offset:34816
	ds_read_b128 v[208:211], v206 offset:35840
	ds_read_b128 v[212:215], v206 offset:36864
	ds_read_b128 v[216:219], v206 offset:37888
	ds_read_b128 v[220:223], v206 offset:38912
	ds_read_b128 v[224:227], v206 offset:39936
	global_load_lds_dwordx4 v[234:235], off
	v_lshl_add_u64 v[234:235], s[48:49], 0, v[166:167]
	s_mov_b32 m0, s67
	s_nop 0
	global_load_lds_dwordx4 v[234:235], off
	s_waitcnt vmcnt(8)
	s_waitcnt lgkmcnt(0)
	s_barrier
	s_setprio 1
	s_waitcnt lgkmcnt(0)
	v_mfma_f32_16x16x32_bf16 v[128:131], v[132:135], v[180:183], v[128:131]
	v_mfma_f32_16x16x32_bf16 v[124:127], v[140:143], v[180:183], v[124:127]
	v_mfma_f32_16x16x32_bf16 v[112:115], v[132:135], v[188:191], v[112:115]
	v_mfma_f32_16x16x32_bf16 v[108:111], v[140:143], v[188:191], v[108:111]
	v_mfma_f32_16x16x32_bf16 v[96:99], v[132:135], v[212:215], v[96:99]
	v_mfma_f32_16x16x32_bf16 v[92:95], v[140:143], v[212:215], v[92:95]
	v_mfma_f32_16x16x32_bf16 v[80:83], v[132:135], v[220:223], v[80:83]
	v_mfma_f32_16x16x32_bf16 v[76:79], v[140:143], v[220:223], v[76:79]
	v_mfma_f32_16x16x32_bf16 v[128:131], v[136:139], v[184:187], v[128:131]
	v_mfma_f32_16x16x32_bf16 v[124:127], v[144:147], v[184:187], v[124:127]
	v_mfma_f32_16x16x32_bf16 v[112:115], v[136:139], v[208:211], v[112:115]
	v_mfma_f32_16x16x32_bf16 v[108:111], v[144:147], v[208:211], v[108:111]
	v_mfma_f32_16x16x32_bf16 v[96:99], v[136:139], v[216:219], v[96:99]
	v_mfma_f32_16x16x32_bf16 v[92:95], v[144:147], v[216:219], v[92:95]
	v_mfma_f32_16x16x32_bf16 v[80:83], v[136:139], v[224:227], v[80:83]
	v_mfma_f32_16x16x32_bf16 v[76:79], v[144:147], v[224:227], v[76:79]
	s_setprio 0
	s_setprio 1
	v_mfma_f32_16x16x32_bf16 v[120:123], v[148:151], v[180:183], v[120:123]
	v_mfma_f32_16x16x32_bf16 v[116:119], v[156:159], v[180:183], v[116:119]
	v_mfma_f32_16x16x32_bf16 v[104:107], v[148:151], v[188:191], v[104:107]
	v_mfma_f32_16x16x32_bf16 v[100:103], v[156:159], v[188:191], v[100:103]
	v_mfma_f32_16x16x32_bf16 v[88:91], v[148:151], v[212:215], v[88:91]
	v_mfma_f32_16x16x32_bf16 v[84:87], v[156:159], v[212:215], v[84:87]
	v_mfma_f32_16x16x32_bf16 v[72:75], v[148:151], v[220:223], v[72:75]
	v_mfma_f32_16x16x32_bf16 v[68:71], v[156:159], v[220:223], v[68:71]
	v_mfma_f32_16x16x32_bf16 v[120:123], v[152:155], v[184:187], v[120:123]
	v_mfma_f32_16x16x32_bf16 v[116:119], v[176:179], v[184:187], v[116:119]
	v_mfma_f32_16x16x32_bf16 v[104:107], v[152:155], v[208:211], v[104:107]
	v_mfma_f32_16x16x32_bf16 v[100:103], v[176:179], v[208:211], v[100:103]
	v_mfma_f32_16x16x32_bf16 v[88:91], v[152:155], v[216:219], v[88:91]
	v_mfma_f32_16x16x32_bf16 v[84:87], v[176:179], v[216:219], v[84:87]
	v_mfma_f32_16x16x32_bf16 v[72:75], v[152:155], v[224:227], v[72:75]
	v_mfma_f32_16x16x32_bf16 v[68:71], v[176:179], v[224:227], v[68:71]
	s_setprio 0
	s_barrier
; #define PG8_STAGE(bufoff, gbase, voff) do { _Pragma("unroll") for (int _i = 0; _i < 2; ++_i) \
;         __builtin_amdgcn_global_load_lds((const unsigned*)((const char*)(gbase) + (voff)[_i]), (PG8_LAS unsigned*)(lds + (bufoff) + ldsw + _i * 8192), 16, 0, 0); } while (0)
; #define PG8_LDA(dst, b, h) do { _Pragma("unroll") for (int m = 0; m < 4; ++m) _Pragma("unroll") for (int k = 0; k < 2; ++k) dst[m][k] = *(const PG8_LAS bf16x8*)(lds + PG8_SA(b, h) + aoff + m * 2048 + k * 1024); } while (0)
; #define PG8_MMA(ai, bj, At, Bt) do { __builtin_amdgcn_s_setprio(1); _Pragma("unroll") for (int m = 0; m < 4; ++m) _Pragma("unroll") for (int n = 0; n < 2; ++n) _Pragma("unroll") for (int k = 0; k < 2; ++k) \
;         acc[ai][bj][m][n] = __builtin_amdgcn_mfma_f32_16x16x32_bf16(Bt[n][k], At[m][k], acc[ai][bj][m][n], 0, 0, 0); __builtin_amdgcn_s_setprio(0); } while (0)
; #define PG8_WAIT_V(n) asm volatile("s_waitcnt vmcnt(" #n ")" ::: "memory")
; #define PG8_WAIT_L(n) asm volatile("s_waitcnt lgkmcnt(" #n ")" ::: "memory")
; #define PG8_BAR __builtin_amdgcn_s_barrier()
; #define PG8_SCHED __builtin_amdgcn_sched_barrier(0)
; template <class Epi, class Sched, bool ALIGN_EPI = false, bool SP2 = false>
; __device__ __forceinline__ void gemm_phase(PG8_LAS unsigned char* lds, const Gemm g, const Sched& S, const Epi& E) {
;     ...
;             PG8_WAIT_V(8); PG8_WAIT_L(0); PG8_BAR; PG8_MMA(0, 0, At, B0); PG8_MMA(0, 1, At, B1); PG8_BAR; PG8_SCHED;
;             PG8_LDA(At, 1, 1); PG8_STAGE(PG8_SB(1, 0), b3, voffB); PG8_STAGE(PG8_SB(1, 1), b3 + hstepB, voffB); PG8_STAGE(PG8_SA(1, 0), a3, voffA);
;             PG8_WAIT_V(8); PG8_WAIT_L(0); PG8_BAR; PG8_MMA(1, 0, At, B0); PG8_MMA(1, 1, At, B1); PG8_BAR; PG8_SCHED;
	s_add_i32 s35, s35, s61
	v_lshl_add_u64 v[192:193], v[192:193], 0, s[52:53]
	s_mov_b32 m0, s35
	ds_read_b128 v[180:183], v206 offset:49152
	ds_read_b128 v[184:187], v206 offset:50176
	ds_read_b128 v[188:191], v206 offset:51200
	ds_read_b128 v[208:211], v206 offset:52224
	ds_read_b128 v[212:215], v206 offset:53248
	ds_read_b128 v[216:219], v206 offset:54272
	ds_read_b128 v[220:223], v206 offset:55296
	ds_read_b128 v[224:227], v206 offset:56320
	global_load_lds_dwordx4 v[192:193], off
	s_add_i32 m0, s35, 0x2000
	s_add_u32 s48, s56, 0xb0080
	v_lshl_add_u64 v[192:193], v[228:229], 0, s[52:53]
	s_addc_u32 s49, s57, 0
	s_add_i32 s35, s73, s61
	global_load_lds_dwordx4 v[192:193], off
	v_lshl_add_u64 v[192:193], s[48:49], 0, v[168:169]
	s_mov_b32 m0, s35
	s_nop 0
	global_load_lds_dwordx4 v[192:193], off
	v_lshl_add_u64 v[192:193], s[48:49], 0, v[164:165]
	s_add_i32 m0, s35, 0x2000
	s_nop 0
	global_load_lds_dwordx4 v[192:193], off
	v_lshl_add_u64 v[192:193], v[230:231], 0, s[52:53]
	s_mov_b32 m0, s24
	s_nop 0
	global_load_lds_dwordx4 v[192:193], off
	v_lshl_add_u64 v[192:193], v[232:233], 0, s[52:53]
	s_mov_b32 m0, s25
	s_nop 0
	global_load_lds_dwordx4 v[192:193], off
	s_waitcnt vmcnt(8)
	s_waitcnt lgkmcnt(0)
	s_barrier
	s_setprio 1
	s_waitcnt lgkmcnt(0)
	v_mfma_f32_16x16x32_bf16 v[62:65], v[132:135], v[180:183], v[62:65]
	v_mfma_f32_16x16x32_bf16 v[58:61], v[140:143], v[180:183], v[58:61]
	v_mfma_f32_16x16x32_bf16 v[46:49], v[132:135], v[188:191], v[46:49]
	v_mfma_f32_16x16x32_bf16 v[42:45], v[140:143], v[188:191], v[42:45]
	v_mfma_f32_16x16x32_bf16 v[30:33], v[132:135], v[212:215], v[30:33]
	v_mfma_f32_16x16x32_bf16 v[26:29], v[140:143], v[212:215], v[26:29]
	v_mfma_f32_16x16x32_bf16 v[14:17], v[132:135], v[220:223], v[14:17]
	v_mfma_f32_16x16x32_bf16 v[10:13], v[140:143], v[220:223], v[10:13]
	v_mfma_f32_16x16x32_bf16 v[62:65], v[136:139], v[184:187], v[62:65]
	v_mfma_f32_16x16x32_bf16 v[58:61], v[144:147], v[184:187], v[58:61]
	v_mfma_f32_16x16x32_bf16 v[46:49], v[136:139], v[208:211], v[46:49]
	v_mfma_f32_16x16x32_bf16 v[42:45], v[144:147], v[208:211], v[42:45]
	v_mfma_f32_16x16x32_bf16 v[30:33], v[136:139], v[216:219], v[30:33]
	v_mfma_f32_16x16x32_bf16 v[26:29], v[144:147], v[216:219], v[26:29]
	v_mfma_f32_16x16x32_bf16 v[14:17], v[136:139], v[224:227], v[14:17]
	v_mfma_f32_16x16x32_bf16 v[10:13], v[144:147], v[224:227], v[10:13]
	s_setprio 0
	s_setprio 1
	v_mfma_f32_16x16x32_bf16 v[54:57], v[148:151], v[180:183], v[54:57]
	v_mfma_f32_16x16x32_bf16 v[50:53], v[156:159], v[180:183], v[50:53]
	v_mfma_f32_16x16x32_bf16 v[38:41], v[148:151], v[188:191], v[38:41]
	v_mfma_f32_16x16x32_bf16 v[34:37], v[156:159], v[188:191], v[34:37]
	v_mfma_f32_16x16x32_bf16 v[22:25], v[148:151], v[212:215], v[22:25]
	v_mfma_f32_16x16x32_bf16 v[18:21], v[156:159], v[212:215], v[18:21]
	v_mfma_f32_16x16x32_bf16 v[6:9], v[148:151], v[220:223], v[6:9]
	v_mfma_f32_16x16x32_bf16 v[2:5], v[156:159], v[220:223], v[2:5]
	v_mfma_f32_16x16x32_bf16 v[54:57], v[152:155], v[184:187], v[54:57]
	v_mfma_f32_16x16x32_bf16 v[50:53], v[176:179], v[184:187], v[50:53]
	v_mfma_f32_16x16x32_bf16 v[38:41], v[152:155], v[208:211], v[38:41]
	v_mfma_f32_16x16x32_bf16 v[34:37], v[176:179], v[208:211], v[34:37]
	v_mfma_f32_16x16x32_bf16 v[22:25], v[152:155], v[216:219], v[22:25]
	v_mfma_f32_16x16x32_bf16 v[18:21], v[176:179], v[216:219], v[18:21]
	v_mfma_f32_16x16x32_bf16 v[6:9], v[152:155], v[224:227], v[6:9]
	v_mfma_f32_16x16x32_bf16 v[2:5], v[176:179], v[224:227], v[2:5]
	s_setprio 0
	s_barrier
	s_add_i32 s34, s34, 2
	s_add_u32 s30, s30, 0x100
	s_addc_u32 s31, s31, 0
	s_cmp_gt_u32 s34, 41
	s_mov_b64 s[48:49], s[50:51]
	s_cbranch_scc0 .LBB0_912
; __device__ __forceinline__ unsigned cvt_pk_bf16(float lo, float hi) { f32x2c v = {lo, hi}; bf16x2c b = __builtin_convertvector(v, bf16x2c); return __builtin_bit_cast(unsigned, b); }
; __device__ __forceinline__ float bf_lo(unsigned w) { return __uint_as_float(w << 16); }
; __device__ __forceinline__ float bf_hi(unsigned w) { return __uint_as_float(w & 0xffff0000u); }
;     __device__ __forceinline__ void operator()(f32x4 (&acc)[2][2][4][2], const Unit& u, int wr, int wc, int fr, int fq) const {
;         const int row0 = u.pm * BM + wr * 64 + fr, col0 = u.pn * BM + wc * 32 + 8 * fq;
; #pragma unroll
;         for (int ai = 0; ai < 2; ++ai) {
;             u32x4 bb[4][2];
; #pragma unroll
;             for (int m = 0; m < 4; ++m)
; #pragma unroll
;                 for (int bj = 0; bj < 2; ++bj) bb[m][bj] = *(const u32x4*)(baseh + (size_t)(row0 + ai * HALF + m * 16) * 1024 + col0 + bj * HALF);
; #pragma unroll
;             for (int m = 0; m < 4; ++m) {
;                 const int row = row0 + ai * HALF + m * 16; float s = 0.f;
; #pragma unroll
;                 for (int bj = 0; bj < 2; ++bj) {
;                     const u32x4 b = bb[m][bj];
;                     const f32x4 v0 = acc[ai][bj][m][0] + (f32x4){bf_lo(b.x), bf_hi(b.x), bf_lo(b.y), bf_hi(b.y)}, v1 = acc[ai][bj][m][1] + (f32x4){bf_lo(b.z), bf_hi(b.z), bf_lo(b.w), bf_hi(b.w)};
;                     s += (v0[0] * v0[0] + v0[1] * v0[1]) + (v0[2] * v0[2] + v0[3] * v0[3]) + (v1[0] * v1[0] + v1[1] * v1[1]) + (v1[2] * v1[2] + v1[3] * v1[3]);
;                     u32x4 w; w.x = cvt_pk_bf16(v0[0], v0[1]); w.y = cvt_pk_bf16(v0[2], v0[3]); w.z = cvt_pk_bf16(v1[0], v1[1]); w.w = cvt_pk_bf16(v1[2], v1[3]);
;                     *(u32x4*)(outh + (size_t)row * 1024 + col0 + bj * HALF) = w;
;                 }
;                 s += __shfl_xor(s, 16); s += __shfl_xor(s, 32);
;                 if (fq == 0) ssq[(size_t)(row >> 8) * pstride + (row & 255) * 16 + u.pn * 4 + wc] = s;
	v_and_b32_e32 v133, 64, v203
	v_xor_b32_e32 v132, 16, v203
	v_add_u32_e32 v133, 64, v133
	s_lshl_b32 s30, s72, 8
	v_cmp_lt_i32_e32 vcc, v132, v133
	s_add_i32 s30, s30, s70
	v_lshl_or_b32 v176, s71, 8, v205
	v_cndmask_b32_e32 v132, v203, v132, vcc
	v_or_b32_e32 v178, s30, v67
	v_ashrrev_i32_e32 v177, 31, v176
	v_lshlrev_b32_e32 v208, 2, v132
	v_xor_b32_e32 v132, 32, v203
	v_cmp_lt_i32_e32 vcc, v132, v133
	v_lshlrev_b64 v[214:215], 1, v[176:177]
	v_ashrrev_i32_e32 v179, 31, v178
	v_cndmask_b32_e32 v132, v203, v132, vcc
	v_lshl_add_u64 v[180:181], s[90:91], 0, v[214:215]
	v_lshlrev_b64 v[216:217], 11, v[178:179]
	v_lshlrev_b32_e32 v207, 2, v132
	v_lshl_add_u64 v[132:133], v[180:181], 0, v[216:217]
	global_load_dwordx4 v[210:213], v[132:133], off
	global_load_dwordx4 v[156:159], v[132:133], off offset:256
	v_or_b32_e32 v190, 16, v178
	v_ashrrev_i32_e32 v191, 31, v190
	v_or_b32_e32 v186, 32, v178
	v_lshlrev_b64 v[192:193], 11, v[190:191]
	v_ashrrev_i32_e32 v187, 31, v186
	v_or_b32_e32 v182, 48, v178
	v_lshl_add_u64 v[132:133], v[180:181], 0, v[192:193]
	v_lshlrev_b64 v[188:189], 11, v[186:187]
	v_ashrrev_i32_e32 v183, 31, v182
	global_load_dwordx4 v[152:155], v[132:133], off
	global_load_dwordx4 v[148:151], v[132:133], off offset:256
	v_lshl_add_u64 v[132:133], v[180:181], 0, v[188:189]
	v_lshlrev_b64 v[184:185], 11, v[182:183]
	global_load_dwordx4 v[144:147], v[132:133], off
	global_load_dwordx4 v[140:143], v[132:133], off offset:256
	v_lshl_add_u64 v[132:133], v[180:181], 0, v[184:185]
	global_load_dwordx4 v[136:139], v[132:133], off
	s_nop 0
	global_load_dwordx4 v[132:135], v[132:133], off offset:256
	v_lshlrev_b32_e32 v209, 4, v0
	v_add_u32_e32 v209, 0x21800, v209
	ds_write_b128 v209, v[172:175]
	s_mov_b64 s[100:101], 0x40000
	v_lshl_add_u64 v[236:237], v[180:181], 0, v[216:217]
	v_lshl_add_u64 v[236:237], v[236:237], 0, s[100:101]
	global_load_dwordx4 v[220:223], v[236:237], off
	global_load_dwordx4 v[224:227], v[236:237], off offset:256
	v_lshl_add_u64 v[236:237], v[180:181], 0, v[192:193]
	v_lshl_add_u64 v[236:237], v[236:237], 0, s[100:101]
	global_load_dwordx4 v[228:231], v[236:237], off
	global_load_dwordx4 v[232:235], v[236:237], off offset:256
	v_lshl_add_u64 v[236:237], v[180:181], 0, v[188:189]
	v_lshl_add_u64 v[236:237], v[236:237], 0, s[100:101]
	global_load_dwordx4 v[244:247], v[236:237], off
	global_load_dwordx4 v[248:251], v[236:237], off offset:256
	v_lshl_add_u64 v[236:237], v[180:181], 0, v[184:185]
	v_lshl_add_u64 v[236:237], v[236:237], 0, s[100:101]
	global_load_dwordx4 v[252:255], v[236:237], off
	global_load_dwordx4 v[172:175], v[236:237], off offset:256
	s_lshl_b32 s48, s71, 2
	s_ashr_i32 s50, s30, 8
	s_ashr_i32 s49, s48, 31
	s_ashr_i32 s51, s50, 31
	s_waitcnt vmcnt(8)
	v_lshlrev_b32_e32 v218, 16, v210
	v_and_b32_e32 v219, 0xffff0000, v210
	v_lshlrev_b32_e32 v210, 16, v211
	v_and_b32_e32 v211, 0xffff0000, v211
	v_pk_add_f32 v[130:131], v[130:131], v[210:211]
	v_pk_add_f32 v[128:129], v[128:129], v[218:219]
	v_lshlrev_b32_e32 v210, 16, v212
	v_and_b32_e32 v211, 0xffff0000, v212
	v_lshlrev_b32_e32 v212, 16, v213
	v_and_b32_e32 v213, 0xffff0000, v213
	v_pk_add_f32 v[212:213], v[126:127], v[212:213]
	v_mul_f32_e32 v126, v129, v129
	v_mul_f32_e32 v127, v131, v131
	v_pk_add_f32 v[124:125], v[124:125], v[210:211]
	v_fmac_f32_e32 v126, v128, v128
	v_fmac_f32_e32 v127, v130, v130
	v_add_f32_e32 v126, v126, v127
	v_mul_f32_e32 v127, v125, v125
	v_fmac_f32_e32 v127, v124, v124
	v_add_f32_e32 v126, v127, v126
	v_mul_f32_e32 v127, v213, v213
	v_fmac_f32_e32 v127, v212, v212
	v_add_f32_e32 v179, v127, v126
	v_cvt_pk_bf16_f32 v126, v128, v129
	v_cvt_pk_bf16_f32 v128, v124, v125
	v_lshl_add_u64 v[124:125], s[90:91], 0, v[216:217]
	v_cvt_pk_bf16_f32 v127, v130, v131
	v_cvt_pk_bf16_f32 v129, v212, v213
	v_lshl_add_u64 v[124:125], v[124:125], 0, v[214:215]
	global_store_dwordx4 v[124:125], v[126:129], off
	s_nop 1
	v_lshlrev_b32_e32 v126, 16, v156
	v_and_b32_e32 v127, 0xffff0000, v156
	v_lshlrev_b32_e32 v128, 16, v157
	v_and_b32_e32 v129, 0xffff0000, v157
	v_pk_add_f32 v[122:123], v[122:123], v[128:129]
	v_pk_add_f32 v[120:121], v[120:121], v[126:127]
	v_lshlrev_b32_e32 v126, 16, v158
	v_and_b32_e32 v127, 0xffff0000, v158
	v_lshlrev_b32_e32 v128, 16, v159
	v_and_b32_e32 v129, 0xffff0000, v159
	v_pk_add_f32 v[128:129], v[118:119], v[128:129]
	v_pk_add_f32 v[118:119], v[116:117], v[126:127]
	v_mul_f32_e32 v116, v121, v121
	v_mul_f32_e32 v117, v123, v123
	v_fmac_f32_e32 v116, v120, v120
	v_fmac_f32_e32 v117, v122, v122
	v_add_f32_e32 v116, v116, v117
	v_mul_f32_e32 v117, v119, v119
	v_fmac_f32_e32 v117, v118, v118
	v_add_f32_e32 v116, v117, v116
	v_mul_f32_e32 v117, v129, v129
	v_fmac_f32_e32 v117, v128, v128
	v_add_f32_e32 v116, v117, v116
	v_add_f32_e32 v126, v179, v116
	v_cvt_pk_bf16_f32 v116, v120, v121
	v_cvt_pk_bf16_f32 v117, v122, v123
	v_cvt_pk_bf16_f32 v118, v118, v119
	v_cvt_pk_bf16_f32 v119, v128, v129
	global_store_dwordx4 v[124:125], v[116:119], off offset:256
	ds_bpermute_b32 v116, v208, v126
	s_waitcnt lgkmcnt(0)
	v_add_f32_e32 v116, v126, v116
	ds_bpermute_b32 v117, v207, v116
	s_and_saveexec_b64 s[56:57], s[36:37]
	s_cbranch_execz .LBB0_915
	s_lshl_b64 s[30:31], s[50:51], s27
	s_lshl_b64 s[30:31], s[30:31], 2
	s_waitcnt lgkmcnt(0)
	v_add_f32_e32 v118, v116, v117
	s_add_u32 s30, s40, s30
	v_lshlrev_b32_e32 v116, 6, v178
	s_addc_u32 s31, s41, s31
	v_and_b32_e32 v116, 0x33c0, v116
	v_mov_b32_e32 v117, v66
	v_lshl_add_u64 v[116:117], s[30:31], 0, v[116:117]
	v_lshl_add_u64 v[116:117], s[48:49], 2, v[116:117]
	s_lshl_b32 s84, s23, 2
	v_lshl_add_u64 v[116:117], v[116:117], 0, s[84:85]
	global_store_dword v[116:117], v118, off

; __device__ __forceinline__ unsigned cvt_pk_bf16(float lo, float hi) { f32x2c v = {lo, hi}; bf16x2c b = __builtin_convertvector(v, bf16x2c); return __builtin_bit_cast(unsigned, b); }
; __device__ __forceinline__ float bf_lo(unsigned w) { return __uint_as_float(w << 16); }
; __device__ __forceinline__ float bf_hi(unsigned w) { return __uint_as_float(w & 0xffff0000u); }
;     __device__ __forceinline__ void operator()(f32x4 (&acc)[2][2][4][2], const Unit& u, int wr, int wc, int fr, int fq) const {
;     ...
;         for (int ai = 0; ai < 2; ++ai) {
;             u32x4 bb[4][2];
; #pragma unroll
;             for (int m = 0; m < 4; ++m)
; #pragma unroll
;                 for (int bj = 0; bj < 2; ++bj) bb[m][bj] = *(const u32x4*)(baseh + (size_t)(row0 + ai * HALF + m * 16) * 1024 + col0 + bj * HALF);
; #pragma unroll
;             for (int m = 0; m < 4; ++m) {
;                 const int row = row0 + ai * HALF + m * 16; float s = 0.f;
; #pragma unroll
;                 for (int bj = 0; bj < 2; ++bj) {
;                     const u32x4 b = bb[m][bj];
;                     const f32x4 v0 = acc[ai][bj][m][0] + (f32x4){bf_lo(b.x), bf_hi(b.x), bf_lo(b.y), bf_hi(b.y)}, v1 = acc[ai][bj][m][1] + (f32x4){bf_lo(b.z), bf_hi(b.z), bf_lo(b.w), bf_hi(b.w)};
;                     s += (v0[0] * v0[0] + v0[1] * v0[1]) + (v0[2] * v0[2] + v0[3] * v0[3]) + (v1[0] * v1[0] + v1[1] * v1[1]) + (v1[2] * v1[2] + v1[3] * v1[3]);
;                     u32x4 w; w.x = cvt_pk_bf16(v0[0], v0[1]); w.y = cvt_pk_bf16(v0[2], v0[3]); w.z = cvt_pk_bf16(v1[0], v1[1]); w.w = cvt_pk_bf16(v1[2], v1[3]);
;                     *(u32x4*)(outh + (size_t)row * 1024 + col0 + bj * HALF) = w;
;                 }
;                 s += __shfl_xor(s, 16); s += __shfl_xor(s, 32);
;                 if (fq == 0) ssq[(size_t)(row >> 8) * pstride + (row & 255) * 16 + u.pn * 4 + wc] = s;
.LBB0_921:
	s_or_b64 exec, exec, s[56:57]
	v_add_u32_e32 v108, 0x80, v178
	v_ashrrev_i32_e32 v109, 31, v108
	v_lshlrev_b64 v[112:113], 11, v[108:109]
	s_waitcnt lgkmcnt(0)
	v_lshl_add_u64 v[68:69], v[180:181], 0, v[112:113]
	s_waitcnt vmcnt(8)
	v_mov_b32_e32 v114, v220
	v_mov_b32_e32 v115, v221
	v_mov_b32_e32 v116, v222
	v_mov_b32_e32 v117, v223
	v_mov_b32_e32 v92, v224
	v_mov_b32_e32 v93, v225
	v_mov_b32_e32 v94, v226
	v_mov_b32_e32 v95, v227
	v_add_u32_e32 v104, 0x90, v178
	v_ashrrev_i32_e32 v105, 31, v104
	v_add_u32_e32 v100, 0xa0, v178
	v_lshlrev_b64 v[106:107], 11, v[104:105]
	v_ashrrev_i32_e32 v101, 31, v100
	v_add_u32_e32 v96, 0xb0, v178
	v_lshl_add_u64 v[68:69], v[180:181], 0, v[106:107]
	v_lshlrev_b64 v[102:103], 11, v[100:101]
	v_ashrrev_i32_e32 v97, 31, v96
	v_mov_b32_e32 v88, v228
	v_mov_b32_e32 v89, v229
	v_mov_b32_e32 v90, v230
	v_mov_b32_e32 v91, v231
	v_mov_b32_e32 v84, v232
	v_mov_b32_e32 v85, v233
	v_mov_b32_e32 v86, v234
	v_mov_b32_e32 v87, v235
	v_lshl_add_u64 v[68:69], v[180:181], 0, v[102:103]
	v_lshlrev_b64 v[98:99], 11, v[96:97]
	v_mov_b32_e32 v80, v244
	v_mov_b32_e32 v81, v245
	v_mov_b32_e32 v82, v246
	v_mov_b32_e32 v83, v247
	v_mov_b32_e32 v76, v248
	v_mov_b32_e32 v77, v249
	v_mov_b32_e32 v78, v250
	v_mov_b32_e32 v79, v251
	v_lshl_add_u64 v[68:69], v[180:181], 0, v[98:99]
	v_mov_b32_e32 v72, v252
	v_mov_b32_e32 v73, v253
	v_mov_b32_e32 v74, v254
	v_mov_b32_e32 v75, v255
	s_nop 0
	v_mov_b32_e32 v68, v172
	v_mov_b32_e32 v69, v173
	v_mov_b32_e32 v70, v174
	v_mov_b32_e32 v71, v175
	ds_read_b128 v[172:175], v209
	s_waitcnt lgkmcnt(0)
	v_ashrrev_i32_e32 v110, 8, v108
	v_ashrrev_i32_e32 v111, 31, v110
	v_lshlrev_b32_e32 v118, 16, v114
	v_and_b32_e32 v119, 0xffff0000, v114
	v_lshlrev_b32_e32 v114, 16, v115
	v_and_b32_e32 v115, 0xffff0000, v115
	v_pk_add_f32 v[64:65], v[64:65], v[114:115]
	v_pk_add_f32 v[62:63], v[62:63], v[118:119]
	v_lshlrev_b32_e32 v114, 16, v116
	v_and_b32_e32 v115, 0xffff0000, v116
	v_lshlrev_b32_e32 v116, 16, v117
	v_and_b32_e32 v117, 0xffff0000, v117
	v_pk_add_f32 v[116:117], v[60:61], v[116:117]
	v_pk_add_f32 v[60:61], v[58:59], v[114:115]
	v_mul_f32_e32 v58, v63, v63
	v_mul_f32_e32 v59, v65, v65
	v_fmac_f32_e32 v58, v62, v62
	v_fmac_f32_e32 v59, v64, v64
	v_add_f32_e32 v58, v58, v59
	v_mul_f32_e32 v59, v61, v61
	v_fmac_f32_e32 v59, v60, v60
	v_add_f32_e32 v58, v59, v58
	v_mul_f32_e32 v59, v117, v117
	v_fmac_f32_e32 v59, v116, v116
	v_add_f32_e32 v97, v59, v58
	v_cvt_pk_bf16_f32 v58, v62, v63
	v_lshl_add_u64 v[62:63], s[90:91], 0, v[112:113]
	v_cvt_pk_bf16_f32 v59, v64, v65
	v_cvt_pk_bf16_f32 v60, v60, v61
	v_cvt_pk_bf16_f32 v61, v116, v117
	v_lshl_add_u64 v[62:63], v[176:177], 1, v[62:63]
	global_store_dwordx4 v[62:63], v[58:61], off
	s_nop 0
	v_lshlrev_b32_e32 v58, 16, v92
	v_and_b32_e32 v59, 0xffff0000, v92
	v_lshlrev_b32_e32 v60, 16, v93
	v_and_b32_e32 v61, 0xffff0000, v93
	v_pk_add_f32 v[56:57], v[56:57], v[60:61]
	v_pk_add_f32 v[54:55], v[54:55], v[58:59]
	v_lshlrev_b32_e32 v58, 16, v94
	v_and_b32_e32 v59, 0xffff0000, v94
	v_lshlrev_b32_e32 v60, 16, v95
	v_and_b32_e32 v61, 0xffff0000, v95
	v_pk_add_f32 v[60:61], v[52:53], v[60:61]
	v_pk_add_f32 v[52:53], v[50:51], v[58:59]
	v_mul_f32_e32 v50, v55, v55
	v_mul_f32_e32 v51, v57, v57
	v_fmac_f32_e32 v50, v54, v54
	v_fmac_f32_e32 v51, v56, v56
	v_add_f32_e32 v50, v50, v51
	v_mul_f32_e32 v51, v53, v53
	v_fmac_f32_e32 v51, v52, v52
	v_add_f32_e32 v50, v51, v50
	v_mul_f32_e32 v51, v61, v61
	v_fmac_f32_e32 v51, v60, v60
	v_add_f32_e32 v50, v51, v50
	v_add_f32_e32 v58, v97, v50
	v_cvt_pk_bf16_f32 v50, v54, v55
	v_cvt_pk_bf16_f32 v51, v56, v57
	v_cvt_pk_bf16_f32 v52, v52, v53
	v_cvt_pk_bf16_f32 v53, v60, v61
	global_store_dwordx4 v[62:63], v[50:53], off offset:256
	ds_bpermute_b32 v50, v208, v58
	s_waitcnt lgkmcnt(0)
	v_add_f32_e32 v52, v58, v50
	ds_bpermute_b32 v53, v207, v52
	v_lshlrev_b64 v[50:51], s27, v[110:111]
	s_and_saveexec_b64 s[50:51], s[36:37]
	s_cbranch_execz .LBB0_923
	v_lshlrev_b32_e32 v54, 6, v108
	s_waitcnt lgkmcnt(0)
	v_add_f32_e32 v56, v52, v53
	v_lshl_add_u64 v[52:53], v[50:51], 2, s[40:41]
	v_and_b32_e32 v54, 0x33c0, v54
	v_mov_b32_e32 v55, v66
	v_lshl_add_u64 v[52:53], v[52:53], 0, v[54:55]
	v_lshl_add_u64 v[52:53], s[48:49], 2, v[52:53]
	s_lshl_b32 s84, s23, 2
	v_lshl_add_u64 v[52:53], v[52:53], 0, s[84:85]
	global_store_dword v[52:53], v56, off
; __device__ __forceinline__ unsigned cvt_pk_bf16(float lo, float hi) { f32x2c v = {lo, hi}; bf16x2c b = __builtin_convertvector(v, bf16x2c); return __builtin_bit_cast(unsigned, b); }
; __device__ __forceinline__ float bf_lo(unsigned w) { return __uint_as_float(w << 16); }
; __device__ __forceinline__ float bf_hi(unsigned w) { return __uint_as_float(w & 0xffff0000u); }
;     __device__ __forceinline__ void operator()(f32x4 (&acc)[2][2][4][2], const Unit& u, int wr, int wc, int fr, int fq) const {
;     ...
;             for (int m = 0; m < 4; ++m) {
;                 const int row = row0 + ai * HALF + m * 16; float s = 0.f;
; #pragma unroll
;                 for (int bj = 0; bj < 2; ++bj) {
;                     const u32x4 b = bb[m][bj];
;                     const f32x4 v0 = acc[ai][bj][m][0] + (f32x4){bf_lo(b.x), bf_hi(b.x), bf_lo(b.y), bf_hi(b.y)}, v1 = acc[ai][bj][m][1] + (f32x4){bf_lo(b.z), bf_hi(b.z), bf_lo(b.w), bf_hi(b.w)};
;                     s += (v0[0] * v0[0] + v0[1] * v0[1]) + (v0[2] * v0[2] + v0[3] * v0[3]) + (v1[0] * v1[0] + v1[1] * v1[1]) + (v1[2] * v1[2] + v1[3] * v1[3]);
;                     u32x4 w; w.x = cvt_pk_bf16(v0[0], v0[1]); w.y = cvt_pk_bf16(v0[2], v0[3]); w.z = cvt_pk_bf16(v1[0], v1[1]); w.w = cvt_pk_bf16(v1[2], v1[3]);
;                     *(u32x4*)(outh + (size_t)row * 1024 + col0 + bj * HALF) = w;
;                 }
;                 s += __shfl_xor(s, 16); s += __shfl_xor(s, 32);
;                 if (fq == 0) ssq[(size_t)(row >> 8) * pstride + (row & 255) * 16 + u.pn * 4 + wc] = s;
.LBB0_923:
	s_or_b64 exec, exec, s[50:51]
	v_lshlrev_b32_e32 v52, 16, v88
	s_waitcnt lgkmcnt(0)
	v_and_b32_e32 v53, 0xffff0000, v88
	v_lshlrev_b32_e32 v54, 16, v89
	v_and_b32_e32 v55, 0xffff0000, v89
	v_pk_add_f32 v[48:49], v[48:49], v[54:55]
	v_pk_add_f32 v[46:47], v[46:47], v[52:53]
	v_lshlrev_b32_e32 v52, 16, v90
	v_and_b32_e32 v53, 0xffff0000, v90
	v_lshlrev_b32_e32 v54, 16, v91
	v_and_b32_e32 v55, 0xffff0000, v91
	v_pk_add_f32 v[54:55], v[44:45], v[54:55]
	v_pk_add_f32 v[44:45], v[42:43], v[52:53]
	v_mul_f32_e32 v42, v47, v47
	v_mul_f32_e32 v43, v49, v49
	v_fmac_f32_e32 v42, v46, v46
	v_fmac_f32_e32 v43, v48, v48
	v_add_f32_e32 v42, v42, v43
	v_mul_f32_e32 v43, v45, v45
	v_fmac_f32_e32 v43, v44, v44
	v_add_f32_e32 v42, v43, v42
	v_mul_f32_e32 v43, v55, v55
	v_fmac_f32_e32 v43, v54, v54
	v_add_f32_e32 v52, v43, v42
	v_cvt_pk_bf16_f32 v42, v46, v47
	v_cvt_pk_bf16_f32 v43, v48, v49
	v_lshlrev_b32_e32 v46, 16, v84
	v_and_b32_e32 v47, 0xffff0000, v84
	v_lshlrev_b32_e32 v48, 16, v85
	v_and_b32_e32 v49, 0xffff0000, v85
	v_pk_add_f32 v[40:41], v[40:41], v[48:49]
	v_pk_add_f32 v[38:39], v[38:39], v[46:47]
	v_lshlrev_b32_e32 v46, 16, v86
	v_and_b32_e32 v47, 0xffff0000, v86
	v_pk_add_f32 v[46:47], v[34:35], v[46:47]
	v_mul_f32_e32 v34, v39, v39
	v_mul_f32_e32 v35, v41, v41
	v_fmac_f32_e32 v34, v38, v38
	v_fmac_f32_e32 v35, v40, v40
	v_lshlrev_b32_e32 v48, 16, v87
	v_and_b32_e32 v49, 0xffff0000, v87
	v_add_f32_e32 v34, v34, v35
	v_mul_f32_e32 v35, v47, v47
	v_pk_add_f32 v[48:49], v[36:37], v[48:49]
	v_fmac_f32_e32 v35, v46, v46
	v_add_f32_e32 v34, v35, v34
	v_mul_f32_e32 v35, v49, v49
	v_fmac_f32_e32 v35, v48, v48
	v_add_f32_e32 v34, v35, v34
	v_add_f32_e32 v37, v52, v34
	v_cvt_pk_bf16_f32 v44, v44, v45
	v_cvt_pk_bf16_f32 v45, v54, v55
	ds_bpermute_b32 v54, v208, v37
	v_lshl_add_u64 v[34:35], s[90:91], 0, v[106:107]
	v_lshl_add_u64 v[52:53], v[176:177], 1, v[34:35]
	v_cvt_pk_bf16_f32 v36, v38, v39
	v_cvt_pk_bf16_f32 v38, v46, v47
	s_waitcnt lgkmcnt(0)
	v_add_f32_e32 v34, v37, v54
	ds_bpermute_b32 v35, v207, v34
	v_cvt_pk_bf16_f32 v37, v40, v41
	v_cvt_pk_bf16_f32 v39, v48, v49
	global_store_dwordx4 v[52:53], v[42:45], off
	global_store_dwordx4 v[52:53], v[36:39], off offset:256
	s_and_saveexec_b64 s[50:51], s[36:37]
	s_cbranch_execz .LBB0_925
	v_lshlrev_b32_e32 v36, 6, v104
	s_waitcnt lgkmcnt(0)
	v_add_f32_e32 v38, v34, v35
	v_lshl_add_u64 v[34:35], v[50:51], 2, s[40:41]
	v_and_b32_e32 v36, 0x37c0, v36
	v_mov_b32_e32 v37, v66
	v_lshl_add_u64 v[34:35], v[34:35], 0, v[36:37]
	v_lshl_add_u64 v[34:35], s[48:49], 2, v[34:35]
	s_lshl_b32 s84, s23, 2
	v_lshl_add_u64 v[34:35], v[34:35], 0, s[84:85]
	global_store_dword v[34:35], v38, off
; __device__ __forceinline__ unsigned cvt_pk_bf16(float lo, float hi) { f32x2c v = {lo, hi}; bf16x2c b = __builtin_convertvector(v, bf16x2c); return __builtin_bit_cast(unsigned, b); }
; __device__ __forceinline__ float bf_lo(unsigned w) { return __uint_as_float(w << 16); }
; __device__ __forceinline__ float bf_hi(unsigned w) { return __uint_as_float(w & 0xffff0000u); }
;     __device__ __forceinline__ void operator()(f32x4 (&acc)[2][2][4][2], const Unit& u, int wr, int wc, int fr, int fq) const {
;     ...
;             for (int m = 0; m < 4; ++m) {
;                 const int row = row0 + ai * HALF + m * 16; float s = 0.f;
; #pragma unroll
;                 for (int bj = 0; bj < 2; ++bj) {
;                     const u32x4 b = bb[m][bj];
;                     const f32x4 v0 = acc[ai][bj][m][0] + (f32x4){bf_lo(b.x), bf_hi(b.x), bf_lo(b.y), bf_hi(b.y)}, v1 = acc[ai][bj][m][1] + (f32x4){bf_lo(b.z), bf_hi(b.z), bf_lo(b.w), bf_hi(b.w)};
;                     s += (v0[0] * v0[0] + v0[1] * v0[1]) + (v0[2] * v0[2] + v0[3] * v0[3]) + (v1[0] * v1[0] + v1[1] * v1[1]) + (v1[2] * v1[2] + v1[3] * v1[3]);
;                     u32x4 w; w.x = cvt_pk_bf16(v0[0], v0[1]); w.y = cvt_pk_bf16(v0[2], v0[3]); w.z = cvt_pk_bf16(v1[0], v1[1]); w.w = cvt_pk_bf16(v1[2], v1[3]);
;                     *(u32x4*)(outh + (size_t)row * 1024 + col0 + bj * HALF) = w;
;                 }
;                 s += __shfl_xor(s, 16); s += __shfl_xor(s, 32);
;                 if (fq == 0) ssq[(size_t)(row >> 8) * pstride + (row & 255) * 16 + u.pn * 4 + wc] = s;
.LBB0_925:
	s_or_b64 exec, exec, s[50:51]
	v_lshlrev_b32_e32 v34, 16, v80
	s_waitcnt lgkmcnt(0)
	v_and_b32_e32 v35, 0xffff0000, v80
	v_lshlrev_b32_e32 v36, 16, v81
	v_and_b32_e32 v37, 0xffff0000, v81
	v_pk_add_f32 v[32:33], v[32:33], v[36:37]
	v_pk_add_f32 v[30:31], v[30:31], v[34:35]
	v_lshlrev_b32_e32 v34, 16, v82
	v_and_b32_e32 v35, 0xffff0000, v82
	v_lshlrev_b32_e32 v36, 16, v83
	v_and_b32_e32 v37, 0xffff0000, v83
	v_pk_add_f32 v[36:37], v[28:29], v[36:37]
	v_pk_add_f32 v[28:29], v[26:27], v[34:35]
	v_mul_f32_e32 v26, v31, v31
	v_mul_f32_e32 v27, v33, v33
	v_fmac_f32_e32 v26, v30, v30
	v_fmac_f32_e32 v27, v32, v32
	v_add_f32_e32 v26, v26, v27
	v_mul_f32_e32 v27, v29, v29
	v_fmac_f32_e32 v27, v28, v28
	v_add_f32_e32 v26, v27, v26
	v_mul_f32_e32 v27, v37, v37
	v_fmac_f32_e32 v27, v36, v36
	v_add_f32_e32 v34, v27, v26
	v_cvt_pk_bf16_f32 v26, v30, v31
	v_cvt_pk_bf16_f32 v27, v32, v33
	v_lshlrev_b32_e32 v30, 16, v76
	v_and_b32_e32 v31, 0xffff0000, v76
	v_lshlrev_b32_e32 v32, 16, v77
	v_and_b32_e32 v33, 0xffff0000, v77
	v_pk_add_f32 v[24:25], v[24:25], v[32:33]
	v_pk_add_f32 v[22:23], v[22:23], v[30:31]
	v_lshlrev_b32_e32 v30, 16, v78
	v_and_b32_e32 v31, 0xffff0000, v78
	v_pk_add_f32 v[30:31], v[18:19], v[30:31]
	v_mul_f32_e32 v18, v23, v23
	v_mul_f32_e32 v19, v25, v25
	v_fmac_f32_e32 v18, v22, v22
	v_fmac_f32_e32 v19, v24, v24
	v_lshlrev_b32_e32 v32, 16, v79
	v_and_b32_e32 v33, 0xffff0000, v79
	v_add_f32_e32 v18, v18, v19
	v_mul_f32_e32 v19, v31, v31
	v_pk_add_f32 v[32:33], v[20:21], v[32:33]
	v_fmac_f32_e32 v19, v30, v30
	v_add_f32_e32 v18, v19, v18
	v_mul_f32_e32 v19, v33, v33
	v_fmac_f32_e32 v19, v32, v32
	v_add_f32_e32 v18, v19, v18
	v_add_f32_e32 v21, v34, v18
	v_cvt_pk_bf16_f32 v28, v28, v29
	v_cvt_pk_bf16_f32 v29, v36, v37
	ds_bpermute_b32 v36, v208, v21
	v_lshl_add_u64 v[18:19], s[90:91], 0, v[102:103]
	v_lshl_add_u64 v[34:35], v[176:177], 1, v[18:19]
	v_cvt_pk_bf16_f32 v20, v22, v23
	v_cvt_pk_bf16_f32 v22, v30, v31
	s_waitcnt lgkmcnt(0)
	v_add_f32_e32 v18, v21, v36
	ds_bpermute_b32 v19, v207, v18
	v_cvt_pk_bf16_f32 v21, v24, v25
	v_cvt_pk_bf16_f32 v23, v32, v33
	global_store_dwordx4 v[34:35], v[26:29], off
	global_store_dwordx4 v[34:35], v[20:23], off offset:256
	s_and_saveexec_b64 s[50:51], s[36:37]
	s_cbranch_execz .LBB0_927
	v_lshlrev_b32_e32 v20, 6, v100
	s_waitcnt lgkmcnt(0)
	v_add_f32_e32 v22, v18, v19
	v_lshl_add_u64 v[18:19], v[50:51], 2, s[40:41]
	v_and_b32_e32 v20, 0x3bc0, v20
	v_mov_b32_e32 v21, v66
	v_lshl_add_u64 v[18:19], v[18:19], 0, v[20:21]
	v_lshl_add_u64 v[18:19], s[48:49], 2, v[18:19]
	s_lshl_b32 s84, s23, 2
	v_lshl_add_u64 v[18:19], v[18:19], 0, s[84:85]
	global_store_dword v[18:19], v22, off
.LBB0_927:
	s_or_b64 exec, exec, s[50:51]
	v_lshlrev_b32_e32 v18, 16, v72
	s_waitcnt lgkmcnt(0)
	v_and_b32_e32 v19, 0xffff0000, v72
	v_lshlrev_b32_e32 v20, 16, v73
	v_and_b32_e32 v21, 0xffff0000, v73
	v_pk_add_f32 v[16:17], v[16:17], v[20:21]
	v_pk_add_f32 v[14:15], v[14:15], v[18:19]
	v_lshlrev_b32_e32 v18, 16, v74
	v_and_b32_e32 v19, 0xffff0000, v74
	v_lshlrev_b32_e32 v20, 16, v75
	v_and_b32_e32 v21, 0xffff0000, v75
	v_pk_add_f32 v[20:21], v[12:13], v[20:21]
	v_pk_add_f32 v[12:13], v[10:11], v[18:19]
	v_mul_f32_e32 v10, v15, v15
	v_mul_f32_e32 v11, v17, v17
	v_fmac_f32_e32 v10, v14, v14
	v_fmac_f32_e32 v11, v16, v16
	v_add_f32_e32 v10, v10, v11
	v_mul_f32_e32 v11, v13, v13
	v_fmac_f32_e32 v11, v12, v12
	v_add_f32_e32 v10, v11, v10
	v_mul_f32_e32 v11, v21, v21
	v_fmac_f32_e32 v11, v20, v20
	v_add_f32_e32 v18, v11, v10
	v_cvt_pk_bf16_f32 v10, v14, v15
	v_cvt_pk_bf16_f32 v11, v16, v17
	v_lshlrev_b32_e32 v14, 16, v68
	v_and_b32_e32 v15, 0xffff0000, v68
	v_lshlrev_b32_e32 v16, 16, v69
	v_and_b32_e32 v17, 0xffff0000, v69
	v_pk_add_f32 v[8:9], v[8:9], v[16:17]
	v_pk_add_f32 v[6:7], v[6:7], v[14:15]
	v_lshlrev_b32_e32 v14, 16, v70
	v_and_b32_e32 v15, 0xffff0000, v70
	v_pk_add_f32 v[14:15], v[2:3], v[14:15]
	v_mul_f32_e32 v2, v7, v7
	v_mul_f32_e32 v3, v9, v9
	v_fmac_f32_e32 v2, v6, v6
	v_fmac_f32_e32 v3, v8, v8
	v_lshlrev_b32_e32 v16, 16, v71
	v_and_b32_e32 v17, 0xffff0000, v71
	v_add_f32_e32 v2, v2, v3
	v_mul_f32_e32 v3, v15, v15
	v_pk_add_f32 v[16:17], v[4:5], v[16:17]
	v_fmac_f32_e32 v3, v14, v14
	v_add_f32_e32 v2, v3, v2
	v_mul_f32_e32 v3, v17, v17
	v_fmac_f32_e32 v3, v16, v16
	v_add_f32_e32 v2, v3, v2
	v_add_f32_e32 v5, v18, v2
	v_cvt_pk_bf16_f32 v12, v12, v13
	v_cvt_pk_bf16_f32 v13, v20, v21
	ds_bpermute_b32 v20, v208, v5
	v_lshl_add_u64 v[2:3], s[90:91], 0, v[98:99]
	v_lshl_add_u64 v[18:19], v[176:177], 1, v[2:3]
	v_cvt_pk_bf16_f32 v4, v6, v7
	v_cvt_pk_bf16_f32 v6, v14, v15
	s_waitcnt lgkmcnt(0)
	v_add_f32_e32 v2, v5, v20
	ds_bpermute_b32 v3, v207, v2
	v_cvt_pk_bf16_f32 v5, v8, v9
	v_cvt_pk_bf16_f32 v7, v16, v17
	global_store_dwordx4 v[18:19], v[10:13], off
	global_store_dwordx4 v[18:19], v[4:7], off offset:256
	s_and_saveexec_b64 s[50:51], s[36:37]
	s_cbranch_execz .LBB0_900
	v_lshlrev_b32_e32 v4, 6, v96
	s_waitcnt lgkmcnt(0)
	v_add_f32_e32 v6, v2, v3
	v_lshl_add_u64 v[2:3], v[50:51], 2, s[40:41]
	v_and_b32_e32 v4, 0x3fc0, v4
	v_mov_b32_e32 v5, v66
	v_lshl_add_u64 v[2:3], v[2:3], 0, v[4:5]
	v_lshl_add_u64 v[2:3], s[48:49], 2, v[2:3]
	s_lshl_b32 s84, s23, 2
	v_lshl_add_u64 v[2:3], v[2:3], 0, s[84:85]
	global_store_dword v[2:3], v6, off
	s_branch .LBB0_900

; __global__ void __launch_bounds__(NWAVES * 64, 2) mk_fwd(Args args) {
	.amdhsa_kernel _Z6mk_fwd4Args
		.amdhsa_group_segment_fixed_size 0
		.amdhsa_private_segment_fixed_size 0
		.amdhsa_kernarg_size 400
		.amdhsa_user_sgpr_count 2
		.amdhsa_user_sgpr_dispatch_ptr 0
		.amdhsa_user_sgpr_queue_ptr 0
		.amdhsa_user_sgpr_kernarg_segment_ptr 1
		.amdhsa_user_sgpr_dispatch_id 0
		.amdhsa_user_sgpr_kernarg_preload_length 0
		.amdhsa_user_sgpr_kernarg_preload_offset 0
		.amdhsa_user_sgpr_private_segment_size 0
		.amdhsa_uses_dynamic_stack 0
		.amdhsa_enable_private_segment 0
		.amdhsa_system_sgpr_workgroup_id_x 1
		.amdhsa_system_sgpr_workgroup_id_y 0
		.amdhsa_system_sgpr_workgroup_id_z 0
		.amdhsa_system_sgpr_workgroup_info 0
		.amdhsa_system_vgpr_workitem_id 0
		.amdhsa_next_free_vgpr 256
		.amdhsa_next_free_sgpr 102
		.amdhsa_accum_offset 256
		.amdhsa_reserve_vcc 1
		.amdhsa_float_round_mode_32 0
		.amdhsa_float_round_mode_16_64 0
		.amdhsa_float_denorm_mode_32 3
		.amdhsa_float_denorm_mode_16_64 3
		.amdhsa_dx10_clamp 1
		.amdhsa_ieee_mode 1
		.amdhsa_fp16_overflow 0
		.amdhsa_tg_split 0
		.amdhsa_exception_fp_ieee_invalid_op 0
		.amdhsa_exception_fp_denorm_src 0
		.amdhsa_exception_fp_ieee_div_zero 0
		.amdhsa_exception_fp_ieee_overflow 0
		.amdhsa_exception_fp_ieee_underflow 0
		.amdhsa_exception_fp_ieee_inexact 0
		.amdhsa_exception_int_div_zero 0
	.end_amdhsa_kernel

; __global__ void __launch_bounds__(NWAVES * 64, 2) mk_fwd(Args args) {
amdhsa.kernels:
  - .agpr_count:     0
    .args:
      - .offset:         0
        .size:           144
        .value_kind:     by_value
      - .offset:         144
        .size:           4
        .value_kind:     hidden_block_count_x
      - .offset:         148
        .size:           4
        .value_kind:     hidden_block_count_y
      - .offset:         152
        .size:           4
        .value_kind:     hidden_block_count_z
      - .offset:         156
        .size:           2
        .value_kind:     hidden_group_size_x
      - .offset:         158
        .size:           2
        .value_kind:     hidden_group_size_y
      - .offset:         160
        .size:           2
        .value_kind:     hidden_group_size_z
      - .offset:         162
        .size:           2
        .value_kind:     hidden_remainder_x
      - .offset:         164
        .size:           2
        .value_kind:     hidden_remainder_y
      - .offset:         166
        .size:           2
        .value_kind:     hidden_remainder_z
      - .offset:         184
        .size:           8
        .value_kind:     hidden_global_offset_x
      - .offset:         192
        .size:           8
        .value_kind:     hidden_global_offset_y
      - .offset:         200
        .size:           8
        .value_kind:     hidden_global_offset_z
      - .offset:         208
        .size:           2
        .value_kind:     hidden_grid_dims
      - .offset:         264
        .size:           4
        .value_kind:     hidden_dynamic_lds_size
    .group_segment_fixed_size: 0
    .kernarg_segment_align: 8
    .kernarg_segment_size: 400
    .language:       OpenCL C
    .language_version:
      - 2
      - 0
    .max_flat_workgroup_size: 512
    .name:           _Z6mk_fwd4Args
    .private_segment_fixed_size: 0
    .sgpr_count:     108
    .sgpr_spill_count: 322
    .symbol:         _Z6mk_fwd4Args.kd
    .uniform_work_group_size: 1
    .uses_dynamic_stack: false
    .vgpr_count:     256
    .vgpr_spill_count: 0
    .wavefront_size: 64
